# removed the s_setprio 0/1 pair between the two 16-MFMA blocks of every K-loop super-phase (on top of the weight prefetch)
# speedup vs baseline: 1.0200x; 1.0043x over previous
; #define PG8_STAGE(bufoff, gbase, voff) do { _Pragma("unroll") for (int _i = 0; _i < 2; ++_i) \
;         __builtin_amdgcn_global_load_lds((const unsigned*)((const char*)(gbase) + (voff)[_i]), (LAS unsigned*)(lds + (bufoff) + ldsw + _i * 8192), 16, 0, 0); } while (0)
; #define PG8_LDA(dst, b, h) do { _Pragma("unroll") for (int m = 0; m < 4; ++m) _Pragma("unroll") for (int k = 0; k < 2; ++k) dst[m][k] = *(const LAS bf16x8*)(lds + PG8_SA(b, h) + aoff + m * 2048 + k * 1024); } while (0)
; #define PG8_LDB(dst, b, h) do { _Pragma("unroll") for (int n = 0; n < 2; ++n) _Pragma("unroll") for (int k = 0; k < 2; ++k) dst[n][k] = *(const LAS bf16x8*)(lds + PG8_SB(b, h) + boff + n * 2048 + k * 1024); } while (0)
; #define PG8_WAIT_V(n) asm volatile("s_waitcnt vmcnt(" #n ")" ::: "memory")
; #define PG8_WAIT_L(n) asm volatile("s_waitcnt lgkmcnt(" #n ")" ::: "memory")
; #define PG8_BAR __builtin_amdgcn_s_barrier()
; #define PG8_SCHED __builtin_amdgcn_sched_barrier(0)
; template <class Epi>
; __device__ __forceinline__ void gemm_phase(LAS unsigned char* lds, const Gemm g, const Order& S, const Epi& E) {
;     ...
;         for (int t = 0; t < nt; t += 2) {
;             const bool last = (t == nt - 2);
;             const char* a1 = cA + (size_t)(t + 1) * kstep;
;             const char* a2 = last ? nA : cA + (size_t)(t + 2) * kstep; const char* b2 = last ? nB : cB + (size_t)(t + 2) * kstep;
;             const char* a3 = a2 + kstep; const char* b3 = b2 + kstep;
;             PG8_LDB(B0, 0, 0); PG8_LDB(B1, 0, 1); PG8_SCHED; PG8_LDA(At, 0, 0); PG8_STAGE(PG8_SA(1, 1), a1 + hstepA, voffA);
;             PG8_WAIT_V(8); PG8_WAIT_L(0); PG8_BAR; PG8_MMA(0, 0, At, B0); PG8_MMA(0, 1, At, B1); PG8_BAR; PG8_SCHED;
;             PG8_LDA(At, 0, 1); PG8_STAGE(PG8_SB(0, 0), b2, voffB); PG8_STAGE(PG8_SB(0, 1), b2 + hstepB, voffB); PG8_STAGE(PG8_SA(0, 0), a2, voffA);
;             PG8_WAIT_V(8); PG8_WAIT_L(0); PG8_BAR; PG8_MMA(1, 0, At, B0); PG8_MMA(1, 1, At, B1); PG8_BAR; PG8_SCHED;
.LBB0_81:
	s_add_u32 s4, s40, 0xfffc0080
	s_addc_u32 s5, s41, -1
	s_add_i32 s6, 0, 0x10000
	s_cmp_eq_u32 vcc_lo, 12
	s_cselect_b32 s71, s34, s5
	s_cselect_b32 s70, s35, s4
	v_add_u32_e32 v142, s6, v145
	s_cselect_b32 s69, s45, s89
	s_cselect_b32 s68, s47, s88
	s_add_i32 s7, 0, 0x14000
	ds_read_b128 v[138:141], v142
	ds_read_b128 v[148:151], v142 offset:1024
	ds_read_b128 v[152:155], v142 offset:2048
	ds_read_b128 v[156:159], v142 offset:3072
	v_add_u32_e32 v142, s7, v145
	ds_read_b128 v[172:175], v142
	ds_read_b128 v[176:179], v142 offset:1024
	ds_read_b128 v[180:183], v142 offset:2048
	ds_read_b128 v[184:187], v142 offset:3072
	v_lshl_add_u64 v[142:143], s[40:41], 0, v[134:135]
	s_add_i32 m0, s24, 0xc000
	ds_read_b128 v[188:191], v147
	ds_read_b128 v[192:195], v147 offset:1024
	ds_read_b128 v[214:217], v147 offset:2048
	ds_read_b128 v[218:221], v147 offset:3072
	ds_read_b128 v[222:225], v147 offset:4096
	ds_read_b128 v[226:229], v147 offset:5120
	ds_read_b128 v[230:233], v147 offset:6144
	ds_read_b128 v[234:237], v147 offset:7168
	global_load_lds_dwordx4 v[142:143], off
	v_lshl_add_u64 v[142:143], s[40:41], 0, v[136:137]
	s_add_i32 m0, s24, 0xe000
	s_nop 0
	global_load_lds_dwordx4 v[142:143], off
	s_waitcnt vmcnt(8)
	s_waitcnt lgkmcnt(0)
	s_barrier
	s_setprio 1
	s_waitcnt lgkmcnt(0)
	v_mfma_f32_16x16x32_f16 v[124:127], v[138:141], v[188:191], v[124:127]
	v_mfma_f32_16x16x32_f16 v[120:123], v[152:155], v[188:191], v[120:123]
	v_mfma_f32_16x16x32_f16 v[108:111], v[138:141], v[214:217], v[108:111]
	v_mfma_f32_16x16x32_f16 v[104:107], v[152:155], v[214:217], v[104:107]
	v_mfma_f32_16x16x32_f16 v[92:95], v[138:141], v[222:225], v[92:95]
	v_mfma_f32_16x16x32_f16 v[88:91], v[152:155], v[222:225], v[88:91]
	v_mfma_f32_16x16x32_f16 v[76:79], v[138:141], v[230:233], v[76:79]
	v_mfma_f32_16x16x32_f16 v[72:75], v[152:155], v[230:233], v[72:75]
	v_mfma_f32_16x16x32_f16 v[124:127], v[148:151], v[192:195], v[124:127]
	v_mfma_f32_16x16x32_f16 v[120:123], v[156:159], v[192:195], v[120:123]
	v_mfma_f32_16x16x32_f16 v[108:111], v[148:151], v[218:221], v[108:111]
	v_mfma_f32_16x16x32_f16 v[104:107], v[156:159], v[218:221], v[104:107]
	v_mfma_f32_16x16x32_f16 v[92:95], v[148:151], v[226:229], v[92:95]
	v_mfma_f32_16x16x32_f16 v[88:91], v[156:159], v[226:229], v[88:91]
	v_mfma_f32_16x16x32_f16 v[76:79], v[148:151], v[234:237], v[76:79]
	v_mfma_f32_16x16x32_f16 v[72:75], v[156:159], v[234:237], v[72:75]
	v_mfma_f32_16x16x32_f16 v[116:119], v[172:175], v[188:191], v[116:119]
	v_mfma_f32_16x16x32_f16 v[112:115], v[180:183], v[188:191], v[112:115]
	v_mfma_f32_16x16x32_f16 v[100:103], v[172:175], v[214:217], v[100:103]
	v_mfma_f32_16x16x32_f16 v[96:99], v[180:183], v[214:217], v[96:99]
	v_mfma_f32_16x16x32_f16 v[84:87], v[172:175], v[222:225], v[84:87]
	v_mfma_f32_16x16x32_f16 v[80:83], v[180:183], v[222:225], v[80:83]
	v_mfma_f32_16x16x32_f16 v[68:71], v[172:175], v[230:233], v[68:71]
	v_mfma_f32_16x16x32_f16 v[64:67], v[180:183], v[230:233], v[64:67]
	v_mfma_f32_16x16x32_f16 v[116:119], v[176:179], v[192:195], v[116:119]
	v_mfma_f32_16x16x32_f16 v[112:115], v[184:187], v[192:195], v[112:115]
	v_mfma_f32_16x16x32_f16 v[100:103], v[176:179], v[218:221], v[100:103]
	v_mfma_f32_16x16x32_f16 v[96:99], v[184:187], v[218:221], v[96:99]
	v_mfma_f32_16x16x32_f16 v[84:87], v[176:179], v[226:229], v[84:87]
	v_mfma_f32_16x16x32_f16 v[80:83], v[184:187], v[226:229], v[80:83]
	v_mfma_f32_16x16x32_f16 v[68:71], v[176:179], v[234:237], v[68:71]
	v_mfma_f32_16x16x32_f16 v[64:67], v[184:187], v[234:237], v[64:67]
	s_setprio 0
	s_barrier
	s_add_i32 s4, s6, s23
	v_lshl_add_u64 v[142:143], s[68:69], 0, v[160:161]
	s_mov_b32 m0, s4
	ds_read_b128 v[188:191], v147 offset:16384
	ds_read_b128 v[192:195], v147 offset:17408
	ds_read_b128 v[214:217], v147 offset:18432
	ds_read_b128 v[218:221], v147 offset:19456
	ds_read_b128 v[222:225], v147 offset:20480
	ds_read_b128 v[226:229], v147 offset:21504
	ds_read_b128 v[230:233], v147 offset:22528
	ds_read_b128 v[234:237], v147 offset:23552
	global_load_lds_dwordx4 v[142:143], off
	s_add_i32 m0, s4, 0x2000
	s_add_u32 s4, s68, 0x40000
	v_lshl_add_u64 v[200:201], s[68:69], 0, v[128:129]
	s_addc_u32 s5, s69, 0
	s_add_i32 s6, s7, s23
	global_load_lds_dwordx4 v[200:201], off
	v_lshl_add_u64 v[238:239], s[4:5], 0, v[160:161]
	s_mov_b32 m0, s6
	v_lshl_add_u64 v[240:241], s[70:71], 0, v[130:131]
	global_load_lds_dwordx4 v[238:239], off
	v_lshl_add_u64 v[238:239], s[4:5], 0, v[128:129]
	s_add_i32 m0, s6, 0x2000
	s_nop 0
	global_load_lds_dwordx4 v[238:239], off
	v_lshl_add_u64 v[238:239], s[70:71], 0, v[132:133]
	s_mov_b32 m0, s24
	s_nop 0
	global_load_lds_dwordx4 v[238:239], off
	s_mov_b32 m0, s25
	s_nop 0
	global_load_lds_dwordx4 v[240:241], off
	s_waitcnt vmcnt(8)
	s_waitcnt lgkmcnt(0)
	s_barrier
; #define PG8_STAGE(bufoff, gbase, voff) do { _Pragma("unroll") for (int _i = 0; _i < 2; ++_i) \
;         __builtin_amdgcn_global_load_lds((const unsigned*)((const char*)(gbase) + (voff)[_i]), (LAS unsigned*)(lds + (bufoff) + ldsw + _i * 8192), 16, 0, 0); } while (0)
; #define PG8_LDA(dst, b, h) do { _Pragma("unroll") for (int m = 0; m < 4; ++m) _Pragma("unroll") for (int k = 0; k < 2; ++k) dst[m][k] = *(const LAS bf16x8*)(lds + PG8_SA(b, h) + aoff + m * 2048 + k * 1024); } while (0)
; #define PG8_LDB(dst, b, h) do { _Pragma("unroll") for (int n = 0; n < 2; ++n) _Pragma("unroll") for (int k = 0; k < 2; ++k) dst[n][k] = *(const LAS bf16x8*)(lds + PG8_SB(b, h) + boff + n * 2048 + k * 1024); } while (0)
; #define PG8_WAIT_V(n) asm volatile("s_waitcnt vmcnt(" #n ")" ::: "memory")
; #define PG8_WAIT_L(n) asm volatile("s_waitcnt lgkmcnt(" #n ")" ::: "memory")
; #define PG8_BAR __builtin_amdgcn_s_barrier()
; #define PG8_SCHED __builtin_amdgcn_sched_barrier(0)
; template <class Epi>
; __device__ __forceinline__ void gemm_phase(LAS unsigned char* lds, const Gemm g, const Order& S, const Epi& E) {
;     ...
;             PG8_WAIT_V(8); PG8_WAIT_L(0); PG8_BAR; PG8_MMA(1, 0, At, B0); PG8_MMA(1, 1, At, B1); PG8_BAR; PG8_SCHED;
;             PG8_LDB(B0, 1, 0); PG8_LDB(B1, 1, 1); PG8_SCHED; PG8_LDA(At, 1, 0); PG8_STAGE(PG8_SA(0, 1), a2 + hstepA, voffA);
;             PG8_WAIT_V(8); PG8_WAIT_L(0); PG8_BAR; PG8_MMA(0, 0, At, B0); PG8_MMA(0, 1, At, B1); PG8_BAR; PG8_SCHED;
	s_setprio 1
	s_waitcnt lgkmcnt(0)
	v_mfma_f32_16x16x32_f16 v[60:63], v[138:141], v[188:191], v[60:63]
	v_mfma_f32_16x16x32_f16 v[56:59], v[152:155], v[188:191], v[56:59]
	v_mfma_f32_16x16x32_f16 v[44:47], v[138:141], v[214:217], v[44:47]
	v_mfma_f32_16x16x32_f16 v[40:43], v[152:155], v[214:217], v[40:43]
	v_mfma_f32_16x16x32_f16 v[28:31], v[138:141], v[222:225], v[28:31]
	v_mfma_f32_16x16x32_f16 v[24:27], v[152:155], v[222:225], v[24:27]
	v_mfma_f32_16x16x32_f16 v[12:15], v[138:141], v[230:233], v[12:15]
	v_mfma_f32_16x16x32_f16 v[8:11], v[152:155], v[230:233], v[8:11]
	v_mfma_f32_16x16x32_f16 v[60:63], v[148:151], v[192:195], v[60:63]
	v_mfma_f32_16x16x32_f16 v[56:59], v[156:159], v[192:195], v[56:59]
	v_mfma_f32_16x16x32_f16 v[44:47], v[148:151], v[218:221], v[44:47]
	v_mfma_f32_16x16x32_f16 v[40:43], v[156:159], v[218:221], v[40:43]
	v_mfma_f32_16x16x32_f16 v[28:31], v[148:151], v[226:229], v[28:31]
	v_mfma_f32_16x16x32_f16 v[24:27], v[156:159], v[226:229], v[24:27]
	v_mfma_f32_16x16x32_f16 v[12:15], v[148:151], v[234:237], v[12:15]
	v_mfma_f32_16x16x32_f16 v[8:11], v[156:159], v[234:237], v[8:11]
	v_mfma_f32_16x16x32_f16 v[52:55], v[172:175], v[188:191], v[52:55]
	v_mfma_f32_16x16x32_f16 v[48:51], v[180:183], v[188:191], v[48:51]
	v_mfma_f32_16x16x32_f16 v[36:39], v[172:175], v[214:217], v[36:39]
	v_mfma_f32_16x16x32_f16 v[32:35], v[180:183], v[214:217], v[32:35]
	v_mfma_f32_16x16x32_f16 v[20:23], v[172:175], v[222:225], v[20:23]
	v_mfma_f32_16x16x32_f16 v[16:19], v[180:183], v[222:225], v[16:19]
	v_mfma_f32_16x16x32_f16 v[4:7], v[172:175], v[230:233], v[4:7]
	v_mfma_f32_16x16x32_f16 v[0:3], v[180:183], v[230:233], v[0:3]
	v_mfma_f32_16x16x32_f16 v[52:55], v[176:179], v[192:195], v[52:55]
	v_mfma_f32_16x16x32_f16 v[48:51], v[184:187], v[192:195], v[48:51]
	v_mfma_f32_16x16x32_f16 v[36:39], v[176:179], v[218:221], v[36:39]
	v_mfma_f32_16x16x32_f16 v[32:35], v[184:187], v[218:221], v[32:35]
	v_mfma_f32_16x16x32_f16 v[20:23], v[176:179], v[226:229], v[20:23]
	v_mfma_f32_16x16x32_f16 v[16:19], v[184:187], v[226:229], v[16:19]
	v_mfma_f32_16x16x32_f16 v[4:7], v[176:179], v[234:237], v[4:7]
	v_mfma_f32_16x16x32_f16 v[0:3], v[184:187], v[234:237], v[0:3]
	s_setprio 0
	s_barrier
	s_add_i32 s6, 0, 0x18000
	s_add_i32 s7, 0, 0x1c000
	v_add_u32_e32 v156, s6, v145
	v_add_u32_e32 v171, s7, v145
	ds_read_b128 v[138:141], v156
	ds_read_b128 v[148:151], v156 offset:1024
	ds_read_b128 v[152:155], v156 offset:2048
	ds_read_b128 v[156:159], v156 offset:3072
	ds_read_b128 v[172:175], v171
	ds_read_b128 v[176:179], v171 offset:1024
	ds_read_b128 v[180:183], v171 offset:2048
	ds_read_b128 v[184:187], v171 offset:3072
	s_add_u32 s4, s70, 0x40000
	s_addc_u32 s5, s71, 0
	s_mov_b32 m0, s26
	v_lshl_add_u64 v[242:243], s[4:5], 0, v[132:133]
	ds_read_b128 v[188:191], v147 offset:32768
	ds_read_b128 v[192:195], v147 offset:33792
	ds_read_b128 v[214:217], v147 offset:34816
	ds_read_b128 v[218:221], v147 offset:35840
	ds_read_b128 v[222:225], v147 offset:36864
	ds_read_b128 v[226:229], v147 offset:37888
	ds_read_b128 v[230:233], v147 offset:38912
	ds_read_b128 v[234:237], v147 offset:39936
	global_load_lds_dwordx4 v[242:243], off
	v_lshl_add_u64 v[242:243], s[4:5], 0, v[130:131]
	s_mov_b32 m0, s27
	s_nop 0
	global_load_lds_dwordx4 v[242:243], off
	s_waitcnt vmcnt(8)
	s_waitcnt lgkmcnt(0)
	s_barrier
	s_setprio 1
	s_waitcnt lgkmcnt(0)
	v_mfma_f32_16x16x32_f16 v[124:127], v[138:141], v[188:191], v[124:127]
	v_mfma_f32_16x16x32_f16 v[120:123], v[152:155], v[188:191], v[120:123]
	v_mfma_f32_16x16x32_f16 v[108:111], v[138:141], v[214:217], v[108:111]
	v_mfma_f32_16x16x32_f16 v[104:107], v[152:155], v[214:217], v[104:107]
	v_mfma_f32_16x16x32_f16 v[92:95], v[138:141], v[222:225], v[92:95]
	v_mfma_f32_16x16x32_f16 v[88:91], v[152:155], v[222:225], v[88:91]
	v_mfma_f32_16x16x32_f16 v[76:79], v[138:141], v[230:233], v[76:79]
	v_mfma_f32_16x16x32_f16 v[72:75], v[152:155], v[230:233], v[72:75]
	v_mfma_f32_16x16x32_f16 v[124:127], v[148:151], v[192:195], v[124:127]
	v_mfma_f32_16x16x32_f16 v[120:123], v[156:159], v[192:195], v[120:123]
	v_mfma_f32_16x16x32_f16 v[108:111], v[148:151], v[218:221], v[108:111]
	v_mfma_f32_16x16x32_f16 v[104:107], v[156:159], v[218:221], v[104:107]
	v_mfma_f32_16x16x32_f16 v[92:95], v[148:151], v[226:229], v[92:95]
	v_mfma_f32_16x16x32_f16 v[88:91], v[156:159], v[226:229], v[88:91]
	v_mfma_f32_16x16x32_f16 v[76:79], v[148:151], v[234:237], v[76:79]
	v_mfma_f32_16x16x32_f16 v[72:75], v[156:159], v[234:237], v[72:75]
	v_mfma_f32_16x16x32_f16 v[116:119], v[172:175], v[188:191], v[116:119]
	v_mfma_f32_16x16x32_f16 v[112:115], v[180:183], v[188:191], v[112:115]
	v_mfma_f32_16x16x32_f16 v[100:103], v[172:175], v[214:217], v[100:103]
	v_mfma_f32_16x16x32_f16 v[96:99], v[180:183], v[214:217], v[96:99]
	v_mfma_f32_16x16x32_f16 v[84:87], v[172:175], v[222:225], v[84:87]
	v_mfma_f32_16x16x32_f16 v[80:83], v[180:183], v[222:225], v[80:83]
	v_mfma_f32_16x16x32_f16 v[68:71], v[172:175], v[230:233], v[68:71]
	v_mfma_f32_16x16x32_f16 v[64:67], v[180:183], v[230:233], v[64:67]
	v_mfma_f32_16x16x32_f16 v[116:119], v[176:179], v[192:195], v[116:119]
	v_mfma_f32_16x16x32_f16 v[112:115], v[184:187], v[192:195], v[112:115]
	v_mfma_f32_16x16x32_f16 v[100:103], v[176:179], v[218:221], v[100:103]
	v_mfma_f32_16x16x32_f16 v[96:99], v[184:187], v[218:221], v[96:99]
	v_mfma_f32_16x16x32_f16 v[84:87], v[176:179], v[226:229], v[84:87]
	v_mfma_f32_16x16x32_f16 v[80:83], v[184:187], v[226:229], v[80:83]
	v_mfma_f32_16x16x32_f16 v[68:71], v[176:179], v[234:237], v[68:71]
	v_mfma_f32_16x16x32_f16 v[64:67], v[184:187], v[234:237], v[64:67]
	s_setprio 0
	s_barrier
; #define PG8_STAGE(bufoff, gbase, voff) do { _Pragma("unroll") for (int _i = 0; _i < 2; ++_i) \
;         __builtin_amdgcn_global_load_lds((const unsigned*)((const char*)(gbase) + (voff)[_i]), (LAS unsigned*)(lds + (bufoff) + ldsw + _i * 8192), 16, 0, 0); } while (0)
; #define PG8_LDA(dst, b, h) do { _Pragma("unroll") for (int m = 0; m < 4; ++m) _Pragma("unroll") for (int k = 0; k < 2; ++k) dst[m][k] = *(const LAS bf16x8*)(lds + PG8_SA(b, h) + aoff + m * 2048 + k * 1024); } while (0)
; #define PG8_WAIT_V(n) asm volatile("s_waitcnt vmcnt(" #n ")" ::: "memory")
; #define PG8_WAIT_L(n) asm volatile("s_waitcnt lgkmcnt(" #n ")" ::: "memory")
; #define PG8_BAR __builtin_amdgcn_s_barrier()
; #define PG8_SCHED __builtin_amdgcn_sched_barrier(0)
; template <class Epi>
; __device__ __forceinline__ void gemm_phase(LAS unsigned char* lds, const Gemm g, const Order& S, const Epi& E) {
;     ...
;             PG8_LDA(At, 1, 1); PG8_STAGE(PG8_SB(1, 0), b3, voffB); PG8_STAGE(PG8_SB(1, 1), b3 + hstepB, voffB); PG8_STAGE(PG8_SA(1, 0), a3, voffA);
;             PG8_WAIT_V(8); PG8_WAIT_L(0); PG8_BAR; PG8_MMA(1, 0, At, B0); PG8_MMA(1, 1, At, B1); PG8_BAR; PG8_SCHED;
;         }
;         if constexpr (ALIGN_EPI) { if (wr == 0) PG8_BAR; }
	s_add_i32 s4, s6, s23
	v_lshl_add_u64 v[142:143], v[142:143], 0, s[62:63]
	s_mov_b32 m0, s4
	ds_read_b128 v[188:191], v147 offset:49152
	ds_read_b128 v[192:195], v147 offset:50176
	ds_read_b128 v[214:217], v147 offset:51200
	ds_read_b128 v[218:221], v147 offset:52224
	ds_read_b128 v[222:225], v147 offset:53248
	ds_read_b128 v[226:229], v147 offset:54272
	ds_read_b128 v[230:233], v147 offset:55296
	ds_read_b128 v[234:237], v147 offset:56320
	global_load_lds_dwordx4 v[142:143], off
	s_add_i32 m0, s4, 0x2000
	s_add_u32 s4, s68, 0x40080
	v_lshl_add_u64 v[142:143], v[200:201], 0, s[62:63]
	s_addc_u32 s5, s69, 0
	s_add_i32 s6, s7, s23
	global_load_lds_dwordx4 v[142:143], off
	v_lshl_add_u64 v[142:143], s[4:5], 0, v[160:161]
	s_mov_b32 m0, s6
	s_nop 0
	global_load_lds_dwordx4 v[142:143], off
	v_lshl_add_u64 v[142:143], s[4:5], 0, v[128:129]
	s_add_i32 m0, s6, 0x2000
	s_nop 0
	global_load_lds_dwordx4 v[142:143], off
	v_lshl_add_u64 v[142:143], v[238:239], 0, s[62:63]
	s_mov_b32 m0, s28
	s_nop 0
	global_load_lds_dwordx4 v[142:143], off
	v_lshl_add_u64 v[142:143], v[240:241], 0, s[62:63]
	s_mov_b32 m0, s29
	s_nop 0
	global_load_lds_dwordx4 v[142:143], off
	s_waitcnt vmcnt(8)
	s_waitcnt lgkmcnt(0)
	s_barrier
	s_setprio 1
	s_waitcnt lgkmcnt(0)
	v_mfma_f32_16x16x32_f16 v[60:63], v[138:141], v[188:191], v[60:63]
	v_mfma_f32_16x16x32_f16 v[56:59], v[152:155], v[188:191], v[56:59]
	v_mfma_f32_16x16x32_f16 v[44:47], v[138:141], v[214:217], v[44:47]
	v_mfma_f32_16x16x32_f16 v[40:43], v[152:155], v[214:217], v[40:43]
	v_mfma_f32_16x16x32_f16 v[28:31], v[138:141], v[222:225], v[28:31]
	v_mfma_f32_16x16x32_f16 v[24:27], v[152:155], v[222:225], v[24:27]
	v_mfma_f32_16x16x32_f16 v[12:15], v[138:141], v[230:233], v[12:15]
	v_mfma_f32_16x16x32_f16 v[8:11], v[152:155], v[230:233], v[8:11]
	v_mfma_f32_16x16x32_f16 v[60:63], v[148:151], v[192:195], v[60:63]
	v_mfma_f32_16x16x32_f16 v[56:59], v[156:159], v[192:195], v[56:59]
	v_mfma_f32_16x16x32_f16 v[44:47], v[148:151], v[218:221], v[44:47]
	v_mfma_f32_16x16x32_f16 v[40:43], v[156:159], v[218:221], v[40:43]
	v_mfma_f32_16x16x32_f16 v[28:31], v[148:151], v[226:229], v[28:31]
	v_mfma_f32_16x16x32_f16 v[24:27], v[156:159], v[226:229], v[24:27]
	v_mfma_f32_16x16x32_f16 v[12:15], v[148:151], v[234:237], v[12:15]
	v_mfma_f32_16x16x32_f16 v[8:11], v[156:159], v[234:237], v[8:11]
	v_mfma_f32_16x16x32_f16 v[52:55], v[172:175], v[188:191], v[52:55]
	v_mfma_f32_16x16x32_f16 v[48:51], v[180:183], v[188:191], v[48:51]
	v_mfma_f32_16x16x32_f16 v[36:39], v[172:175], v[214:217], v[36:39]
	v_mfma_f32_16x16x32_f16 v[32:35], v[180:183], v[214:217], v[32:35]
	v_mfma_f32_16x16x32_f16 v[20:23], v[172:175], v[222:225], v[20:23]
	v_mfma_f32_16x16x32_f16 v[16:19], v[180:183], v[222:225], v[16:19]
	v_mfma_f32_16x16x32_f16 v[4:7], v[172:175], v[230:233], v[4:7]
	v_mfma_f32_16x16x32_f16 v[0:3], v[180:183], v[230:233], v[0:3]
	v_mfma_f32_16x16x32_f16 v[52:55], v[176:179], v[192:195], v[52:55]
	v_mfma_f32_16x16x32_f16 v[48:51], v[184:187], v[192:195], v[48:51]
	v_mfma_f32_16x16x32_f16 v[36:39], v[176:179], v[218:221], v[36:39]
	v_mfma_f32_16x16x32_f16 v[32:35], v[184:187], v[218:221], v[32:35]
	v_mfma_f32_16x16x32_f16 v[20:23], v[176:179], v[226:229], v[20:23]
	v_mfma_f32_16x16x32_f16 v[16:19], v[184:187], v[226:229], v[16:19]
	v_mfma_f32_16x16x32_f16 v[4:7], v[176:179], v[234:237], v[4:7]
	v_mfma_f32_16x16x32_f16 v[0:3], v[184:187], v[234:237], v[0:3]
	s_setprio 0
	s_barrier
	s_add_i32 vcc_lo, vcc_lo, 2
	s_add_u32 s40, s40, 0x100
	s_addc_u32 s41, s41, 0
	s_add_u32 s88, s88, 0x100
	s_addc_u32 s89, s89, 0
	s_cmp_gt_u32 vcc_lo, 13
	s_cbranch_scc0 .LBB0_81
	s_and_b64 vcc, exec, s[42:43]
	s_cbranch_vccz .LBB0_84
	s_barrier

; #define PG8_STAGE(bufoff, gbase, voff) do { _Pragma("unroll") for (int _i = 0; _i < 2; ++_i) \
;         __builtin_amdgcn_global_load_lds((const unsigned*)((const char*)(gbase) + (voff)[_i]), (LAS unsigned*)(lds + (bufoff) + ldsw + _i * 8192), 16, 0, 0); } while (0)
; #define PG8_LDA(dst, b, h) do { _Pragma("unroll") for (int m = 0; m < 4; ++m) _Pragma("unroll") for (int k = 0; k < 2; ++k) dst[m][k] = *(const LAS bf16x8*)(lds + PG8_SA(b, h) + aoff + m * 2048 + k * 1024); } while (0)
; #define PG8_LDB(dst, b, h) do { _Pragma("unroll") for (int n = 0; n < 2; ++n) _Pragma("unroll") for (int k = 0; k < 2; ++k) dst[n][k] = *(const LAS bf16x8*)(lds + PG8_SB(b, h) + boff + n * 2048 + k * 1024); } while (0)
; #define PG8_WAIT_V(n) asm volatile("s_waitcnt vmcnt(" #n ")" ::: "memory")
; #define PG8_WAIT_L(n) asm volatile("s_waitcnt lgkmcnt(" #n ")" ::: "memory")
; #define PG8_BAR __builtin_amdgcn_s_barrier()
; #define PG8_SCHED __builtin_amdgcn_sched_barrier(0)
; template <class Epi>
; __device__ __forceinline__ void gemm_phase(LAS unsigned char* lds, const Gemm g, const Order& S, const Epi& E) {
;     ...
;         for (int t = 0; t < nt; t += 2) {
;             const bool last = (t == nt - 2);
;             const char* a1 = cA + (size_t)(t + 1) * kstep;
;             const char* a2 = last ? nA : cA + (size_t)(t + 2) * kstep; const char* b2 = last ? nB : cB + (size_t)(t + 2) * kstep;
;             const char* a3 = a2 + kstep; const char* b3 = b2 + kstep;
;             PG8_LDB(B0, 0, 0); PG8_LDB(B1, 0, 1); PG8_SCHED; PG8_LDA(At, 0, 0); PG8_STAGE(PG8_SA(1, 1), a1 + hstepA, voffA);
;             PG8_WAIT_V(8); PG8_WAIT_L(0); PG8_BAR; PG8_MMA(0, 0, At, B0); PG8_MMA(0, 1, At, B1); PG8_BAR; PG8_SCHED;
;             PG8_LDA(At, 0, 1); PG8_STAGE(PG8_SB(0, 0), b2, voffB); PG8_STAGE(PG8_SB(0, 1), b2 + hstepB, voffB); PG8_STAGE(PG8_SA(0, 0), a2, voffA);
;             PG8_WAIT_V(8); PG8_WAIT_L(0); PG8_BAR; PG8_MMA(1, 0, At, B0); PG8_MMA(1, 1, At, B1); PG8_BAR; PG8_SCHED;
.LBB0_172:
	s_add_i32 s36, s35, 2
	s_add_u32 s4, s70, vcc_lo
	s_addc_u32 s5, s71, vcc_hi
	s_add_u32 s37, s68, vcc_lo
	s_addc_u32 s6, s69, vcc_hi
	s_add_i32 s7, 0, 0x10000
	s_cmp_eq_u32 s49, s35
	s_cselect_b32 s65, s45, s5
	s_cselect_b32 s64, s44, s4
	v_add_u32_e32 v158, s7, v143
	s_cselect_b32 s5, s89, s6
	s_cselect_b32 s4, s88, s37
	s_add_i32 s6, 0, 0x14000
	ds_read_b128 v[146:149], v158
	ds_read_b128 v[150:153], v158 offset:1024
	ds_read_b128 v[154:157], v158 offset:2048
	ds_read_b128 v[172:175], v158 offset:3072
	v_add_u32_e32 v158, s6, v143
	ds_read_b128 v[176:179], v158
	ds_read_b128 v[180:183], v158 offset:1024
	ds_read_b128 v[184:187], v158 offset:2048
	ds_read_b128 v[188:191], v158 offset:3072
	v_lshl_add_u64 v[158:159], s[70:71], 0, v[140:141]
	s_add_i32 m0, s67, 0xc000
	ds_read_b128 v[192:195], v144
	ds_read_b128 v[214:217], v144 offset:1024
	ds_read_b128 v[218:221], v144 offset:2048
	ds_read_b128 v[222:225], v144 offset:3072
	ds_read_b128 v[226:229], v144 offset:4096
	ds_read_b128 v[230:233], v144 offset:5120
	ds_read_b128 v[234:237], v144 offset:6144
	ds_read_b128 v[238:241], v144 offset:7168
	global_load_lds_dwordx4 v[158:159], off
	v_lshl_add_u64 v[158:159], s[70:71], 0, v[138:139]
	s_add_i32 m0, s67, 0xe000
	s_nop 0
	global_load_lds_dwordx4 v[158:159], off
	s_waitcnt vmcnt(8)
	s_waitcnt lgkmcnt(0)
	s_barrier
	s_setprio 1
	s_waitcnt lgkmcnt(0)
	v_mfma_f32_16x16x32_bf16 v[28:31], v[146:149], v[192:195], v[28:31]
	v_mfma_f32_16x16x32_bf16 v[24:27], v[154:157], v[192:195], v[24:27]
	v_mfma_f32_16x16x32_bf16 v[20:23], v[146:149], v[218:221], v[20:23]
	v_mfma_f32_16x16x32_bf16 v[16:19], v[154:157], v[218:221], v[16:19]
	v_mfma_f32_16x16x32_bf16 v[76:79], v[146:149], v[226:229], v[76:79]
	v_mfma_f32_16x16x32_bf16 v[72:75], v[154:157], v[226:229], v[72:75]
	v_mfma_f32_16x16x32_bf16 v[92:95], v[146:149], v[234:237], v[92:95]
	v_mfma_f32_16x16x32_bf16 v[88:91], v[154:157], v[234:237], v[88:91]
	v_mfma_f32_16x16x32_bf16 v[28:31], v[150:153], v[214:217], v[28:31]
	v_mfma_f32_16x16x32_bf16 v[24:27], v[172:175], v[214:217], v[24:27]
	v_mfma_f32_16x16x32_bf16 v[20:23], v[150:153], v[222:225], v[20:23]
	v_mfma_f32_16x16x32_bf16 v[16:19], v[172:175], v[222:225], v[16:19]
	v_mfma_f32_16x16x32_bf16 v[76:79], v[150:153], v[230:233], v[76:79]
	v_mfma_f32_16x16x32_bf16 v[72:75], v[172:175], v[230:233], v[72:75]
	v_mfma_f32_16x16x32_bf16 v[92:95], v[150:153], v[238:241], v[92:95]
	v_mfma_f32_16x16x32_bf16 v[88:91], v[172:175], v[238:241], v[88:91]
	v_mfma_f32_16x16x32_bf16 v[12:15], v[176:179], v[192:195], v[12:15]
	v_mfma_f32_16x16x32_bf16 v[8:11], v[184:187], v[192:195], v[8:11]
	v_mfma_f32_16x16x32_bf16 v[4:7], v[176:179], v[218:221], v[4:7]
	v_mfma_f32_16x16x32_bf16 v[0:3], v[184:187], v[218:221], v[0:3]
	v_mfma_f32_16x16x32_bf16 v[68:71], v[176:179], v[226:229], v[68:71]
	v_mfma_f32_16x16x32_bf16 v[64:67], v[184:187], v[226:229], v[64:67]
	v_mfma_f32_16x16x32_bf16 v[84:87], v[176:179], v[234:237], v[84:87]
	v_mfma_f32_16x16x32_bf16 v[80:83], v[184:187], v[234:237], v[80:83]
	v_mfma_f32_16x16x32_bf16 v[12:15], v[180:183], v[214:217], v[12:15]
	v_mfma_f32_16x16x32_bf16 v[8:11], v[188:191], v[214:217], v[8:11]
	v_mfma_f32_16x16x32_bf16 v[4:7], v[180:183], v[222:225], v[4:7]
	v_mfma_f32_16x16x32_bf16 v[0:3], v[188:191], v[222:225], v[0:3]
	v_mfma_f32_16x16x32_bf16 v[68:71], v[180:183], v[230:233], v[68:71]
	v_mfma_f32_16x16x32_bf16 v[64:67], v[188:191], v[230:233], v[64:67]
	v_mfma_f32_16x16x32_bf16 v[84:87], v[180:183], v[238:241], v[84:87]
	v_mfma_f32_16x16x32_bf16 v[80:83], v[188:191], v[238:241], v[80:83]
	s_setprio 0
	s_barrier
	s_add_i32 s7, s7, s29
	v_lshl_add_u64 v[158:159], s[4:5], 0, v[160:161]
	s_mov_b32 m0, s7
	ds_read_b128 v[192:195], v144 offset:16384
	ds_read_b128 v[214:217], v144 offset:17408
	ds_read_b128 v[218:221], v144 offset:18432
	ds_read_b128 v[222:225], v144 offset:19456
	ds_read_b128 v[226:229], v144 offset:20480
	ds_read_b128 v[230:233], v144 offset:21504
	ds_read_b128 v[234:237], v144 offset:22528
	ds_read_b128 v[238:241], v144 offset:23552
	global_load_lds_dwordx4 v[158:159], off
	s_add_i32 m0, s7, 0x2000
	v_lshl_add_u64 v[242:243], s[4:5], 0, v[128:129]
	s_add_u32 s4, s4, s28
	s_addc_u32 s5, s5, 0
	s_add_i32 s6, s6, s29
	global_load_lds_dwordx4 v[242:243], off
	v_lshl_add_u64 v[244:245], s[4:5], 0, v[160:161]
	s_mov_b32 m0, s6
	v_lshl_add_u64 v[246:247], s[4:5], 0, v[128:129]
	global_load_lds_dwordx4 v[244:245], off
	s_add_i32 m0, s6, 0x2000
	v_lshl_add_u64 v[248:249], s[64:65], 0, v[132:133]
	global_load_lds_dwordx4 v[246:247], off
	s_mov_b32 m0, s67
	v_lshl_add_u64 v[250:251], s[64:65], 0, v[130:131]
	global_load_lds_dwordx4 v[248:249], off
	s_mov_b32 m0, s82
	s_nop 0
	global_load_lds_dwordx4 v[250:251], off
	s_waitcnt vmcnt(8)
	s_waitcnt lgkmcnt(0)
	s_barrier
; #define PG8_STAGE(bufoff, gbase, voff) do { _Pragma("unroll") for (int _i = 0; _i < 2; ++_i) \
;         __builtin_amdgcn_global_load_lds((const unsigned*)((const char*)(gbase) + (voff)[_i]), (LAS unsigned*)(lds + (bufoff) + ldsw + _i * 8192), 16, 0, 0); } while (0)
; #define PG8_LDA(dst, b, h) do { _Pragma("unroll") for (int m = 0; m < 4; ++m) _Pragma("unroll") for (int k = 0; k < 2; ++k) dst[m][k] = *(const LAS bf16x8*)(lds + PG8_SA(b, h) + aoff + m * 2048 + k * 1024); } while (0)
; #define PG8_LDB(dst, b, h) do { _Pragma("unroll") for (int n = 0; n < 2; ++n) _Pragma("unroll") for (int k = 0; k < 2; ++k) dst[n][k] = *(const LAS bf16x8*)(lds + PG8_SB(b, h) + boff + n * 2048 + k * 1024); } while (0)
; #define PG8_WAIT_V(n) asm volatile("s_waitcnt vmcnt(" #n ")" ::: "memory")
; #define PG8_WAIT_L(n) asm volatile("s_waitcnt lgkmcnt(" #n ")" ::: "memory")
; #define PG8_BAR __builtin_amdgcn_s_barrier()
; #define PG8_SCHED __builtin_amdgcn_sched_barrier(0)
; template <class Epi>
; __device__ __forceinline__ void gemm_phase(LAS unsigned char* lds, const Gemm g, const Order& S, const Epi& E) {
;     ...
;             PG8_WAIT_V(8); PG8_WAIT_L(0); PG8_BAR; PG8_MMA(1, 0, At, B0); PG8_MMA(1, 1, At, B1); PG8_BAR; PG8_SCHED;
;             PG8_LDB(B0, 1, 0); PG8_LDB(B1, 1, 1); PG8_SCHED; PG8_LDA(At, 1, 0); PG8_STAGE(PG8_SA(0, 1), a2 + hstepA, voffA);
;             PG8_WAIT_V(8); PG8_WAIT_L(0); PG8_BAR; PG8_MMA(0, 0, At, B0); PG8_MMA(0, 1, At, B1); PG8_BAR; PG8_SCHED;
	s_setprio 1
	s_waitcnt lgkmcnt(0)
	v_mfma_f32_16x16x32_bf16 v[124:127], v[146:149], v[192:195], v[124:127]
	v_mfma_f32_16x16x32_bf16 v[120:123], v[154:157], v[192:195], v[120:123]
	v_mfma_f32_16x16x32_bf16 v[116:119], v[146:149], v[218:221], v[116:119]
	v_mfma_f32_16x16x32_bf16 v[112:115], v[154:157], v[218:221], v[112:115]
	v_mfma_f32_16x16x32_bf16 v[60:63], v[146:149], v[226:229], v[60:63]
	v_mfma_f32_16x16x32_bf16 v[56:59], v[154:157], v[226:229], v[56:59]
	v_mfma_f32_16x16x32_bf16 v[52:55], v[146:149], v[234:237], v[52:55]
	v_mfma_f32_16x16x32_bf16 v[48:51], v[154:157], v[234:237], v[48:51]
	v_mfma_f32_16x16x32_bf16 v[124:127], v[150:153], v[214:217], v[124:127]
	v_mfma_f32_16x16x32_bf16 v[120:123], v[172:175], v[214:217], v[120:123]
	v_mfma_f32_16x16x32_bf16 v[116:119], v[150:153], v[222:225], v[116:119]
	v_mfma_f32_16x16x32_bf16 v[112:115], v[172:175], v[222:225], v[112:115]
	v_mfma_f32_16x16x32_bf16 v[60:63], v[150:153], v[230:233], v[60:63]
	v_mfma_f32_16x16x32_bf16 v[56:59], v[172:175], v[230:233], v[56:59]
	v_mfma_f32_16x16x32_bf16 v[52:55], v[150:153], v[238:241], v[52:55]
	v_mfma_f32_16x16x32_bf16 v[48:51], v[172:175], v[238:241], v[48:51]
	v_mfma_f32_16x16x32_bf16 v[108:111], v[176:179], v[192:195], v[108:111]
	v_mfma_f32_16x16x32_bf16 v[104:107], v[184:187], v[192:195], v[104:107]
	v_mfma_f32_16x16x32_bf16 v[100:103], v[176:179], v[218:221], v[100:103]
	v_mfma_f32_16x16x32_bf16 v[96:99], v[184:187], v[218:221], v[96:99]
	v_mfma_f32_16x16x32_bf16 v[44:47], v[176:179], v[226:229], v[44:47]
	v_mfma_f32_16x16x32_bf16 v[40:43], v[184:187], v[226:229], v[40:43]
	v_mfma_f32_16x16x32_bf16 v[36:39], v[176:179], v[234:237], v[36:39]
	v_mfma_f32_16x16x32_bf16 v[32:35], v[184:187], v[234:237], v[32:35]
	v_mfma_f32_16x16x32_bf16 v[108:111], v[180:183], v[214:217], v[108:111]
	v_mfma_f32_16x16x32_bf16 v[104:107], v[188:191], v[214:217], v[104:107]
	v_mfma_f32_16x16x32_bf16 v[100:103], v[180:183], v[222:225], v[100:103]
	v_mfma_f32_16x16x32_bf16 v[96:99], v[188:191], v[222:225], v[96:99]
	v_mfma_f32_16x16x32_bf16 v[44:47], v[180:183], v[230:233], v[44:47]
	v_mfma_f32_16x16x32_bf16 v[40:43], v[188:191], v[230:233], v[40:43]
	v_mfma_f32_16x16x32_bf16 v[36:39], v[180:183], v[238:241], v[36:39]
	v_mfma_f32_16x16x32_bf16 v[32:35], v[188:191], v[238:241], v[32:35]
	s_setprio 0
	s_barrier
	s_add_i32 s6, 0, 0x18000
	s_add_i32 s7, 0, 0x1c000
	v_add_u32_e32 v172, s6, v143
	v_add_u32_e32 v188, s7, v143
	ds_read_b128 v[146:149], v172
	ds_read_b128 v[150:153], v172 offset:1024
	ds_read_b128 v[154:157], v172 offset:2048
	ds_read_b128 v[172:175], v172 offset:3072
	ds_read_b128 v[176:179], v188
	ds_read_b128 v[180:183], v188 offset:1024
	ds_read_b128 v[184:187], v188 offset:2048
	ds_read_b128 v[188:191], v188 offset:3072
	s_add_u32 s4, s64, s28
	s_addc_u32 s5, s65, 0
	s_mov_b32 m0, s46
	v_lshl_add_u64 v[200:201], s[4:5], 0, v[132:133]
	ds_read_b128 v[192:195], v144 offset:32768
	ds_read_b128 v[214:217], v144 offset:33792
	ds_read_b128 v[218:221], v144 offset:34816
	ds_read_b128 v[222:225], v144 offset:35840
	ds_read_b128 v[226:229], v144 offset:36864
	ds_read_b128 v[230:233], v144 offset:37888
	ds_read_b128 v[234:237], v144 offset:38912
	ds_read_b128 v[238:241], v144 offset:39936
	global_load_lds_dwordx4 v[200:201], off
	v_lshl_add_u64 v[200:201], s[4:5], 0, v[130:131]
	s_mov_b32 m0, s47
	s_nop 0
	global_load_lds_dwordx4 v[200:201], off
	s_waitcnt vmcnt(8)
	s_waitcnt lgkmcnt(0)
	s_barrier
	s_setprio 1
	s_waitcnt lgkmcnt(0)
	v_mfma_f32_16x16x32_bf16 v[28:31], v[146:149], v[192:195], v[28:31]
	v_mfma_f32_16x16x32_bf16 v[24:27], v[154:157], v[192:195], v[24:27]
	v_mfma_f32_16x16x32_bf16 v[20:23], v[146:149], v[218:221], v[20:23]
	v_mfma_f32_16x16x32_bf16 v[16:19], v[154:157], v[218:221], v[16:19]
	v_mfma_f32_16x16x32_bf16 v[76:79], v[146:149], v[226:229], v[76:79]
	v_mfma_f32_16x16x32_bf16 v[72:75], v[154:157], v[226:229], v[72:75]
	v_mfma_f32_16x16x32_bf16 v[92:95], v[146:149], v[234:237], v[92:95]
	v_mfma_f32_16x16x32_bf16 v[88:91], v[154:157], v[234:237], v[88:91]
	v_mfma_f32_16x16x32_bf16 v[28:31], v[150:153], v[214:217], v[28:31]
	v_mfma_f32_16x16x32_bf16 v[24:27], v[172:175], v[214:217], v[24:27]
	v_mfma_f32_16x16x32_bf16 v[20:23], v[150:153], v[222:225], v[20:23]
	v_mfma_f32_16x16x32_bf16 v[16:19], v[172:175], v[222:225], v[16:19]
	v_mfma_f32_16x16x32_bf16 v[76:79], v[150:153], v[230:233], v[76:79]
	v_mfma_f32_16x16x32_bf16 v[72:75], v[172:175], v[230:233], v[72:75]
	v_mfma_f32_16x16x32_bf16 v[92:95], v[150:153], v[238:241], v[92:95]
	v_mfma_f32_16x16x32_bf16 v[88:91], v[172:175], v[238:241], v[88:91]
	v_mfma_f32_16x16x32_bf16 v[12:15], v[176:179], v[192:195], v[12:15]
	v_mfma_f32_16x16x32_bf16 v[8:11], v[184:187], v[192:195], v[8:11]
	v_mfma_f32_16x16x32_bf16 v[4:7], v[176:179], v[218:221], v[4:7]
	v_mfma_f32_16x16x32_bf16 v[0:3], v[184:187], v[218:221], v[0:3]
	v_mfma_f32_16x16x32_bf16 v[68:71], v[176:179], v[226:229], v[68:71]
	v_mfma_f32_16x16x32_bf16 v[64:67], v[184:187], v[226:229], v[64:67]
	v_mfma_f32_16x16x32_bf16 v[84:87], v[176:179], v[234:237], v[84:87]
	v_mfma_f32_16x16x32_bf16 v[80:83], v[184:187], v[234:237], v[80:83]
	v_mfma_f32_16x16x32_bf16 v[12:15], v[180:183], v[214:217], v[12:15]
	v_mfma_f32_16x16x32_bf16 v[8:11], v[188:191], v[214:217], v[8:11]
	v_mfma_f32_16x16x32_bf16 v[4:7], v[180:183], v[222:225], v[4:7]
	v_mfma_f32_16x16x32_bf16 v[0:3], v[188:191], v[222:225], v[0:3]
	v_mfma_f32_16x16x32_bf16 v[68:71], v[180:183], v[230:233], v[68:71]
	v_mfma_f32_16x16x32_bf16 v[64:67], v[188:191], v[230:233], v[64:67]
	v_mfma_f32_16x16x32_bf16 v[84:87], v[180:183], v[238:241], v[84:87]
	v_mfma_f32_16x16x32_bf16 v[80:83], v[188:191], v[238:241], v[80:83]
	s_setprio 0
	s_barrier
; #define PG8_STAGE(bufoff, gbase, voff) do { _Pragma("unroll") for (int _i = 0; _i < 2; ++_i) \
;         __builtin_amdgcn_global_load_lds((const unsigned*)((const char*)(gbase) + (voff)[_i]), (LAS unsigned*)(lds + (bufoff) + ldsw + _i * 8192), 16, 0, 0); } while (0)
; #define PG8_LDA(dst, b, h) do { _Pragma("unroll") for (int m = 0; m < 4; ++m) _Pragma("unroll") for (int k = 0; k < 2; ++k) dst[m][k] = *(const LAS bf16x8*)(lds + PG8_SA(b, h) + aoff + m * 2048 + k * 1024); } while (0)
; #define PG8_WAIT_V(n) asm volatile("s_waitcnt vmcnt(" #n ")" ::: "memory")
; #define PG8_WAIT_L(n) asm volatile("s_waitcnt lgkmcnt(" #n ")" ::: "memory")
; #define PG8_BAR __builtin_amdgcn_s_barrier()
; #define PG8_SCHED __builtin_amdgcn_sched_barrier(0)
; template <class Epi>
; __device__ __forceinline__ void gemm_phase(LAS unsigned char* lds, const Gemm g, const Order& S, const Epi& E) {
;     ...
;             PG8_LDA(At, 1, 1); PG8_STAGE(PG8_SB(1, 0), b3, voffB); PG8_STAGE(PG8_SB(1, 1), b3 + hstepB, voffB); PG8_STAGE(PG8_SA(1, 0), a3, voffA);
;             PG8_WAIT_V(8); PG8_WAIT_L(0); PG8_BAR; PG8_MMA(1, 0, At, B0); PG8_MMA(1, 1, At, B1); PG8_BAR; PG8_SCHED;
;         }
;         if constexpr (ALIGN_EPI) { if (wr == 0) PG8_BAR; }
;         if constexpr (!Epi::AFTER_DRAIN) E(acc, cur, wr, wc, fr, fq);
;         if (!has_next) break;
;         if (!(Epi::KEEP_ACC && nxt.z != 0)) {
; #pragma unroll
;         for (int a = 0; a < 2; ++a)
; #pragma unroll
;             for (int b = 0; b < 2; ++b)
; #pragma unroll
;                 for (int m = 0; m < 4; ++m)
; #pragma unroll
;                     for (int n = 0; n < 2; ++n) acc[a][b][m][n] = (f32x4){0.f, 0.f, 0.f, 0.f};
;         }
;         cur = nxt; cA = nA; cB = nB; ++ui;
;         if constexpr (ALIGN_EPI) { if (wr == 1) PG8_BAR; }
;     }
	s_add_i32 s4, s6, s29
	v_lshl_add_u64 v[158:159], v[158:159], 0, s[62:63]
	s_mov_b32 m0, s4
	ds_read_b128 v[192:195], v144 offset:49152
	ds_read_b128 v[214:217], v144 offset:50176
	ds_read_b128 v[218:221], v144 offset:51200
	ds_read_b128 v[222:225], v144 offset:52224
	ds_read_b128 v[226:229], v144 offset:53248
	ds_read_b128 v[230:233], v144 offset:54272
	ds_read_b128 v[234:237], v144 offset:55296
	ds_read_b128 v[238:241], v144 offset:56320
	global_load_lds_dwordx4 v[158:159], off
	v_lshl_add_u64 v[158:159], v[242:243], 0, s[62:63]
	s_add_i32 m0, s4, 0x2000
	s_add_i32 s4, s7, s29
	global_load_lds_dwordx4 v[158:159], off
	v_lshl_add_u64 v[158:159], v[244:245], 0, s[62:63]
	s_mov_b32 m0, s4
	s_nop 0
	global_load_lds_dwordx4 v[158:159], off
	v_lshl_add_u64 v[158:159], v[246:247], 0, s[62:63]
	s_add_i32 m0, s4, 0x2000
	s_nop 0
	global_load_lds_dwordx4 v[158:159], off
	v_lshl_add_u64 v[158:159], v[248:249], 0, s[62:63]
	s_mov_b32 m0, s50
	s_nop 0
	global_load_lds_dwordx4 v[158:159], off
	v_lshl_add_u64 v[158:159], v[250:251], 0, s[62:63]
	s_mov_b32 m0, s51
	s_nop 0
	global_load_lds_dwordx4 v[158:159], off
	s_waitcnt vmcnt(8)
	s_waitcnt lgkmcnt(0)
	s_barrier
	s_setprio 1
	s_waitcnt lgkmcnt(0)
	v_mfma_f32_16x16x32_bf16 v[124:127], v[146:149], v[192:195], v[124:127]
	v_mfma_f32_16x16x32_bf16 v[120:123], v[154:157], v[192:195], v[120:123]
	v_mfma_f32_16x16x32_bf16 v[116:119], v[146:149], v[218:221], v[116:119]
	v_mfma_f32_16x16x32_bf16 v[112:115], v[154:157], v[218:221], v[112:115]
	v_mfma_f32_16x16x32_bf16 v[60:63], v[146:149], v[226:229], v[60:63]
	v_mfma_f32_16x16x32_bf16 v[56:59], v[154:157], v[226:229], v[56:59]
	v_mfma_f32_16x16x32_bf16 v[52:55], v[146:149], v[234:237], v[52:55]
	v_mfma_f32_16x16x32_bf16 v[48:51], v[154:157], v[234:237], v[48:51]
	v_mfma_f32_16x16x32_bf16 v[124:127], v[150:153], v[214:217], v[124:127]
	v_mfma_f32_16x16x32_bf16 v[120:123], v[172:175], v[214:217], v[120:123]
	v_mfma_f32_16x16x32_bf16 v[116:119], v[150:153], v[222:225], v[116:119]
	v_mfma_f32_16x16x32_bf16 v[112:115], v[172:175], v[222:225], v[112:115]
	v_mfma_f32_16x16x32_bf16 v[60:63], v[150:153], v[230:233], v[60:63]
	v_mfma_f32_16x16x32_bf16 v[56:59], v[172:175], v[230:233], v[56:59]
	v_mfma_f32_16x16x32_bf16 v[52:55], v[150:153], v[238:241], v[52:55]
	v_mfma_f32_16x16x32_bf16 v[48:51], v[172:175], v[238:241], v[48:51]
	v_mfma_f32_16x16x32_bf16 v[108:111], v[176:179], v[192:195], v[108:111]
	v_mfma_f32_16x16x32_bf16 v[104:107], v[184:187], v[192:195], v[104:107]
	v_mfma_f32_16x16x32_bf16 v[100:103], v[176:179], v[218:221], v[100:103]
	v_mfma_f32_16x16x32_bf16 v[96:99], v[184:187], v[218:221], v[96:99]
	v_mfma_f32_16x16x32_bf16 v[44:47], v[176:179], v[226:229], v[44:47]
	v_mfma_f32_16x16x32_bf16 v[40:43], v[184:187], v[226:229], v[40:43]
	v_mfma_f32_16x16x32_bf16 v[36:39], v[176:179], v[234:237], v[36:39]
	v_mfma_f32_16x16x32_bf16 v[32:35], v[184:187], v[234:237], v[32:35]
	v_mfma_f32_16x16x32_bf16 v[108:111], v[180:183], v[214:217], v[108:111]
	v_mfma_f32_16x16x32_bf16 v[104:107], v[188:191], v[214:217], v[104:107]
	v_mfma_f32_16x16x32_bf16 v[100:103], v[180:183], v[222:225], v[100:103]
	v_mfma_f32_16x16x32_bf16 v[96:99], v[188:191], v[222:225], v[96:99]
	v_mfma_f32_16x16x32_bf16 v[44:47], v[180:183], v[230:233], v[44:47]
	v_mfma_f32_16x16x32_bf16 v[40:43], v[188:191], v[230:233], v[40:43]
	v_mfma_f32_16x16x32_bf16 v[36:39], v[180:183], v[238:241], v[36:39]
	v_mfma_f32_16x16x32_bf16 v[32:35], v[188:191], v[238:241], v[32:35]
	s_setprio 0
	s_barrier
	s_add_u32 vcc_lo, vcc_lo, 0x100
	s_addc_u32 vcc_hi, vcc_hi, 0
	v_lshl_add_u64 v[140:141], v[140:141], 0, s[60:61]
	v_lshl_add_u64 v[138:139], v[138:139], 0, s[60:61]
	s_cmp_ge_u32 s36, s8
	s_mov_b32 s35, s36
	s_cbranch_scc0 .LBB0_172
	s_and_b64 vcc, exec, s[42:43]
	s_cbranch_vccnz .LBB0_160
	v_mov_b32_e32 v32, 0
	s_mov_b32 s66, s30
	s_mov_b32 s9, s31
	s_mov_b64 s[68:69], s[88:89]
	s_mov_b64 s[70:71], s[44:45]
	s_mov_b32 s34, s22
	v_mov_b32_e32 v33, v32
	v_mov_b32_e32 v34, v32
	v_mov_b32_e32 v35, v32
	v_mov_b32_e32 v36, v32
	v_mov_b32_e32 v37, v32
	v_mov_b32_e32 v38, v32
	v_mov_b32_e32 v39, v32
	v_mov_b32_e32 v40, v32
	v_mov_b32_e32 v41, v32
	v_mov_b32_e32 v42, v32
	v_mov_b32_e32 v43, v32
	v_mov_b32_e32 v44, v32
	v_mov_b32_e32 v45, v32
	v_mov_b32_e32 v46, v32
	v_mov_b32_e32 v47, v32
	v_mov_b32_e32 v96, v32
	v_mov_b32_e32 v97, v32
	v_mov_b32_e32 v98, v32
	v_mov_b32_e32 v99, v32
	v_mov_b32_e32 v100, v32
	v_mov_b32_e32 v101, v32
	v_mov_b32_e32 v102, v32
	v_mov_b32_e32 v103, v32
	v_mov_b32_e32 v104, v32
	v_mov_b32_e32 v105, v32
	v_mov_b32_e32 v106, v32
	v_mov_b32_e32 v107, v32
	v_mov_b32_e32 v108, v32
	v_mov_b32_e32 v109, v32
	v_mov_b32_e32 v110, v32
	v_mov_b32_e32 v111, v32
	v_mov_b32_e32 v48, v32
	v_mov_b32_e32 v49, v32
	v_mov_b32_e32 v50, v32
	v_mov_b32_e32 v51, v32
	v_mov_b32_e32 v52, v32
	v_mov_b32_e32 v53, v32
	v_mov_b32_e32 v54, v32
	v_mov_b32_e32 v55, v32
	v_mov_b32_e32 v56, v32
	v_mov_b32_e32 v57, v32
	v_mov_b32_e32 v58, v32
	v_mov_b32_e32 v59, v32
	v_mov_b32_e32 v60, v32
	v_mov_b32_e32 v61, v32
	v_mov_b32_e32 v62, v32
	v_mov_b32_e32 v63, v32
	v_mov_b32_e32 v112, v32
	v_mov_b32_e32 v113, v32
	v_mov_b32_e32 v114, v32
	v_mov_b32_e32 v115, v32
	v_mov_b32_e32 v116, v32
	v_mov_b32_e32 v117, v32
	v_mov_b32_e32 v118, v32
	v_mov_b32_e32 v119, v32
	v_mov_b32_e32 v120, v32
	v_mov_b32_e32 v121, v32
	v_mov_b32_e32 v122, v32
	v_mov_b32_e32 v123, v32
	v_mov_b32_e32 v124, v32
	v_mov_b32_e32 v125, v32
	v_mov_b32_e32 v126, v32
	v_mov_b32_e32 v127, v32
	v_mov_b32_e32 v80, v32
	v_mov_b32_e32 v81, v32
	v_mov_b32_e32 v82, v32
	v_mov_b32_e32 v83, v32
	v_mov_b32_e32 v84, v32
	v_mov_b32_e32 v85, v32
	v_mov_b32_e32 v86, v32
	v_mov_b32_e32 v87, v32
	v_mov_b32_e32 v64, v32
	v_mov_b32_e32 v65, v32
	v_mov_b32_e32 v66, v32
	v_mov_b32_e32 v67, v32
	v_mov_b32_e32 v68, v32
	v_mov_b32_e32 v69, v32
	v_mov_b32_e32 v70, v32
	v_mov_b32_e32 v71, v32
	v_mov_b32_e32 v0, v32
	v_mov_b32_e32 v1, v32
	v_mov_b32_e32 v2, v32
	v_mov_b32_e32 v3, v32
	v_mov_b32_e32 v4, v32
	v_mov_b32_e32 v5, v32
	v_mov_b32_e32 v6, v32
	v_mov_b32_e32 v7, v32
	v_mov_b32_e32 v8, v32
	v_mov_b32_e32 v9, v32
	v_mov_b32_e32 v10, v32
	v_mov_b32_e32 v11, v32
	v_mov_b32_e32 v12, v32
	v_mov_b32_e32 v13, v32
	v_mov_b32_e32 v14, v32
	v_mov_b32_e32 v15, v32
	v_mov_b32_e32 v88, v32
	v_mov_b32_e32 v89, v32
	v_mov_b32_e32 v90, v32
	v_mov_b32_e32 v91, v32
	v_mov_b32_e32 v92, v32
	v_mov_b32_e32 v93, v32
	v_mov_b32_e32 v94, v32
	v_mov_b32_e32 v95, v32
	v_mov_b32_e32 v72, v32
	v_mov_b32_e32 v73, v32
	v_mov_b32_e32 v74, v32
	v_mov_b32_e32 v75, v32
	v_mov_b32_e32 v76, v32
	v_mov_b32_e32 v77, v32
	v_mov_b32_e32 v78, v32
	v_mov_b32_e32 v79, v32
	v_mov_b32_e32 v16, v32
	v_mov_b32_e32 v17, v32
	v_mov_b32_e32 v18, v32
	v_mov_b32_e32 v19, v32
	v_mov_b32_e32 v20, v32
	v_mov_b32_e32 v21, v32
	v_mov_b32_e32 v22, v32
	v_mov_b32_e32 v23, v32
	v_mov_b32_e32 v24, v32
	v_mov_b32_e32 v25, v32
	v_mov_b32_e32 v26, v32
	v_mov_b32_e32 v27, v32
	v_mov_b32_e32 v28, v32
	v_mov_b32_e32 v29, v32
	v_mov_b32_e32 v30, v32
	v_mov_b32_e32 v31, v32
	s_branch .LBB0_160

; #define PG8_STAGE(bufoff, gbase, voff) do { _Pragma("unroll") for (int _i = 0; _i < 2; ++_i) \
;         __builtin_amdgcn_global_load_lds((const unsigned*)((const char*)(gbase) + (voff)[_i]), (LAS unsigned*)(lds + (bufoff) + ldsw + _i * 8192), 16, 0, 0); } while (0)
; #define PG8_LDA(dst, b, h) do { _Pragma("unroll") for (int m = 0; m < 4; ++m) _Pragma("unroll") for (int k = 0; k < 2; ++k) dst[m][k] = *(const LAS bf16x8*)(lds + PG8_SA(b, h) + aoff + m * 2048 + k * 1024); } while (0)
; #define PG8_LDB(dst, b, h) do { _Pragma("unroll") for (int n = 0; n < 2; ++n) _Pragma("unroll") for (int k = 0; k < 2; ++k) dst[n][k] = *(const LAS bf16x8*)(lds + PG8_SB(b, h) + boff + n * 2048 + k * 1024); } while (0)
; #define PG8_WAIT_V(n) asm volatile("s_waitcnt vmcnt(" #n ")" ::: "memory")
; #define PG8_WAIT_L(n) asm volatile("s_waitcnt lgkmcnt(" #n ")" ::: "memory")
; #define PG8_BAR __builtin_amdgcn_s_barrier()
; #define PG8_SCHED __builtin_amdgcn_sched_barrier(0)
; template <class Epi>
; __device__ __forceinline__ void gemm_phase(LAS unsigned char* lds, const Gemm g, const Order& S, const Epi& E) {
;     ...
;         for (int t = 0; t < nt; t += 2) {
;             const bool last = (t == nt - 2);
;             const char* a1 = cA + (size_t)(t + 1) * kstep;
;             const char* a2 = last ? nA : cA + (size_t)(t + 2) * kstep; const char* b2 = last ? nB : cB + (size_t)(t + 2) * kstep;
;             const char* a3 = a2 + kstep; const char* b3 = b2 + kstep;
;             PG8_LDB(B0, 0, 0); PG8_LDB(B1, 0, 1); PG8_SCHED; PG8_LDA(At, 0, 0); PG8_STAGE(PG8_SA(1, 1), a1 + hstepA, voffA);
;             PG8_WAIT_V(8); PG8_WAIT_L(0); PG8_BAR; PG8_MMA(0, 0, At, B0); PG8_MMA(0, 1, At, B1); PG8_BAR; PG8_SCHED;
;             PG8_LDA(At, 0, 1); PG8_STAGE(PG8_SB(0, 0), b2, voffB); PG8_STAGE(PG8_SB(0, 1), b2 + hstepB, voffB); PG8_STAGE(PG8_SA(0, 0), a2, voffA);
;             PG8_WAIT_V(8); PG8_WAIT_L(0); PG8_BAR; PG8_MMA(1, 0, At, B0); PG8_MMA(1, 1, At, B1); PG8_BAR; PG8_SCHED;
.LBB0_281:
	s_add_u32 s40, s64, 0x100
	s_addc_u32 s41, s65, 0
	s_add_i32 s4, 0, 0x10000
	s_cmp_eq_u32 s47, 4
	s_cselect_b32 s69, s49, s41
	s_cselect_b32 s68, s48, s40
	s_cselect_b32 s67, s34, s45
	s_cselect_b32 s66, s35, s43
	s_add_i32 s6, 0, 0x14000
	v_add_u32_e32 v150, s4, v184
	v_add_u32_e32 v158, s6, v184
	ds_read_b128 v[138:141], v150
	ds_read_b128 v[142:145], v150 offset:1024
	ds_read_b128 v[146:149], v150 offset:2048
	ds_read_b128 v[150:153], v150 offset:3072
	ds_read_b128 v[154:157], v158
	ds_read_b128 v[172:175], v158 offset:1024
	ds_read_b128 v[176:179], v158 offset:2048
	ds_read_b128 v[180:183], v158 offset:3072
	v_lshl_add_u64 v[158:159], s[64:65], 0, v[134:135]
	s_add_i32 m0, s25, 0xc000
	ds_read_b128 v[188:191], v186
	ds_read_b128 v[192:195], v186 offset:1024
	ds_read_b128 v[214:217], v186 offset:2048
	ds_read_b128 v[218:221], v186 offset:3072
	ds_read_b128 v[222:225], v186 offset:4096
	ds_read_b128 v[226:229], v186 offset:5120
	ds_read_b128 v[230:233], v186 offset:6144
	ds_read_b128 v[234:237], v186 offset:7168
	global_load_lds_dwordx4 v[158:159], off
	v_lshl_add_u64 v[158:159], s[64:65], 0, v[136:137]
	s_add_i32 m0, s25, 0xe000
	s_nop 0
	global_load_lds_dwordx4 v[158:159], off
	s_waitcnt vmcnt(8)
	s_waitcnt lgkmcnt(0)
	s_barrier
	s_setprio 1
	s_waitcnt lgkmcnt(0)
	v_mfma_f32_16x16x32_bf16 v[124:127], v[138:141], v[188:191], v[124:127]
	v_mfma_f32_16x16x32_bf16 v[120:123], v[146:149], v[188:191], v[120:123]
	v_mfma_f32_16x16x32_bf16 v[116:119], v[138:141], v[214:217], v[116:119]
	v_mfma_f32_16x16x32_bf16 v[112:115], v[146:149], v[214:217], v[112:115]
	v_mfma_f32_16x16x32_bf16 v[108:111], v[138:141], v[222:225], v[108:111]
	v_mfma_f32_16x16x32_bf16 v[104:107], v[146:149], v[222:225], v[104:107]
	v_mfma_f32_16x16x32_bf16 v[100:103], v[138:141], v[230:233], v[100:103]
	v_mfma_f32_16x16x32_bf16 v[96:99], v[146:149], v[230:233], v[96:99]
	v_mfma_f32_16x16x32_bf16 v[124:127], v[142:145], v[192:195], v[124:127]
	v_mfma_f32_16x16x32_bf16 v[120:123], v[150:153], v[192:195], v[120:123]
	v_mfma_f32_16x16x32_bf16 v[116:119], v[142:145], v[218:221], v[116:119]
	v_mfma_f32_16x16x32_bf16 v[112:115], v[150:153], v[218:221], v[112:115]
	v_mfma_f32_16x16x32_bf16 v[108:111], v[142:145], v[226:229], v[108:111]
	v_mfma_f32_16x16x32_bf16 v[104:107], v[150:153], v[226:229], v[104:107]
	v_mfma_f32_16x16x32_bf16 v[100:103], v[142:145], v[234:237], v[100:103]
	v_mfma_f32_16x16x32_bf16 v[96:99], v[150:153], v[234:237], v[96:99]
	v_mfma_f32_16x16x32_bf16 v[92:95], v[154:157], v[188:191], v[92:95]
	v_mfma_f32_16x16x32_bf16 v[88:91], v[176:179], v[188:191], v[88:91]
	v_mfma_f32_16x16x32_bf16 v[84:87], v[154:157], v[214:217], v[84:87]
	v_mfma_f32_16x16x32_bf16 v[80:83], v[176:179], v[214:217], v[80:83]
	v_mfma_f32_16x16x32_bf16 v[76:79], v[154:157], v[222:225], v[76:79]
	v_mfma_f32_16x16x32_bf16 v[72:75], v[176:179], v[222:225], v[72:75]
	v_mfma_f32_16x16x32_bf16 v[68:71], v[154:157], v[230:233], v[68:71]
	v_mfma_f32_16x16x32_bf16 v[64:67], v[176:179], v[230:233], v[64:67]
	v_mfma_f32_16x16x32_bf16 v[92:95], v[172:175], v[192:195], v[92:95]
	v_mfma_f32_16x16x32_bf16 v[88:91], v[180:183], v[192:195], v[88:91]
	v_mfma_f32_16x16x32_bf16 v[84:87], v[172:175], v[218:221], v[84:87]
	v_mfma_f32_16x16x32_bf16 v[80:83], v[180:183], v[218:221], v[80:83]
	v_mfma_f32_16x16x32_bf16 v[76:79], v[172:175], v[226:229], v[76:79]
	v_mfma_f32_16x16x32_bf16 v[72:75], v[180:183], v[226:229], v[72:75]
	v_mfma_f32_16x16x32_bf16 v[68:71], v[172:175], v[234:237], v[68:71]
	v_mfma_f32_16x16x32_bf16 v[64:67], v[180:183], v[234:237], v[64:67]
	s_setprio 0
	s_barrier
	s_add_i32 s4, s4, s24
	v_lshl_add_u64 v[158:159], s[66:67], 0, v[160:161]
	s_mov_b32 m0, s4
	ds_read_b128 v[188:191], v186 offset:16384
	ds_read_b128 v[192:195], v186 offset:17408
	ds_read_b128 v[214:217], v186 offset:18432
	ds_read_b128 v[218:221], v186 offset:19456
	ds_read_b128 v[222:225], v186 offset:20480
	ds_read_b128 v[226:229], v186 offset:21504
	ds_read_b128 v[230:233], v186 offset:22528
	ds_read_b128 v[234:237], v186 offset:23552
	global_load_lds_dwordx4 v[158:159], off
	s_add_i32 m0, s4, 0x2000
	s_add_u32 s4, s66, 0x20000
	v_lshl_add_u64 v[200:201], s[66:67], 0, v[128:129]
	s_addc_u32 s5, s67, 0
	s_add_i32 s6, s6, s24
	global_load_lds_dwordx4 v[200:201], off
	v_lshl_add_u64 v[238:239], s[4:5], 0, v[160:161]
	s_mov_b32 m0, s6
	v_lshl_add_u64 v[240:241], s[68:69], 0, v[130:131]
	global_load_lds_dwordx4 v[238:239], off
	v_lshl_add_u64 v[238:239], s[4:5], 0, v[128:129]
	s_add_i32 m0, s6, 0x2000
	s_nop 0
	global_load_lds_dwordx4 v[238:239], off
	v_lshl_add_u64 v[238:239], s[68:69], 0, v[132:133]
	s_mov_b32 m0, s25
	s_nop 0
	global_load_lds_dwordx4 v[238:239], off
	s_mov_b32 m0, s26
	s_nop 0
	global_load_lds_dwordx4 v[240:241], off
	s_waitcnt vmcnt(8)
	s_waitcnt lgkmcnt(0)
	s_barrier
; #define PG8_STAGE(bufoff, gbase, voff) do { _Pragma("unroll") for (int _i = 0; _i < 2; ++_i) \
;         __builtin_amdgcn_global_load_lds((const unsigned*)((const char*)(gbase) + (voff)[_i]), (LAS unsigned*)(lds + (bufoff) + ldsw + _i * 8192), 16, 0, 0); } while (0)
; #define PG8_LDA(dst, b, h) do { _Pragma("unroll") for (int m = 0; m < 4; ++m) _Pragma("unroll") for (int k = 0; k < 2; ++k) dst[m][k] = *(const LAS bf16x8*)(lds + PG8_SA(b, h) + aoff + m * 2048 + k * 1024); } while (0)
; #define PG8_LDB(dst, b, h) do { _Pragma("unroll") for (int n = 0; n < 2; ++n) _Pragma("unroll") for (int k = 0; k < 2; ++k) dst[n][k] = *(const LAS bf16x8*)(lds + PG8_SB(b, h) + boff + n * 2048 + k * 1024); } while (0)
; #define PG8_WAIT_V(n) asm volatile("s_waitcnt vmcnt(" #n ")" ::: "memory")
; #define PG8_WAIT_L(n) asm volatile("s_waitcnt lgkmcnt(" #n ")" ::: "memory")
; #define PG8_BAR __builtin_amdgcn_s_barrier()
; #define PG8_SCHED __builtin_amdgcn_sched_barrier(0)
; template <class Epi>
; __device__ __forceinline__ void gemm_phase(LAS unsigned char* lds, const Gemm g, const Order& S, const Epi& E) {
;     ...
;             PG8_WAIT_V(8); PG8_WAIT_L(0); PG8_BAR; PG8_MMA(1, 0, At, B0); PG8_MMA(1, 1, At, B1); PG8_BAR; PG8_SCHED;
;             PG8_LDB(B0, 1, 0); PG8_LDB(B1, 1, 1); PG8_SCHED; PG8_LDA(At, 1, 0); PG8_STAGE(PG8_SA(0, 1), a2 + hstepA, voffA);
;             PG8_WAIT_V(8); PG8_WAIT_L(0); PG8_BAR; PG8_MMA(0, 0, At, B0); PG8_MMA(0, 1, At, B1); PG8_BAR; PG8_SCHED;
	s_setprio 1
	s_waitcnt lgkmcnt(0)
	v_mfma_f32_16x16x32_bf16 v[60:63], v[138:141], v[188:191], v[60:63]
	v_mfma_f32_16x16x32_bf16 v[56:59], v[146:149], v[188:191], v[56:59]
	v_mfma_f32_16x16x32_bf16 v[52:55], v[138:141], v[214:217], v[52:55]
	v_mfma_f32_16x16x32_bf16 v[48:51], v[146:149], v[214:217], v[48:51]
	v_mfma_f32_16x16x32_bf16 v[44:47], v[138:141], v[222:225], v[44:47]
	v_mfma_f32_16x16x32_bf16 v[40:43], v[146:149], v[222:225], v[40:43]
	v_mfma_f32_16x16x32_bf16 v[36:39], v[138:141], v[230:233], v[36:39]
	v_mfma_f32_16x16x32_bf16 v[32:35], v[146:149], v[230:233], v[32:35]
	v_mfma_f32_16x16x32_bf16 v[60:63], v[142:145], v[192:195], v[60:63]
	v_mfma_f32_16x16x32_bf16 v[56:59], v[150:153], v[192:195], v[56:59]
	v_mfma_f32_16x16x32_bf16 v[52:55], v[142:145], v[218:221], v[52:55]
	v_mfma_f32_16x16x32_bf16 v[48:51], v[150:153], v[218:221], v[48:51]
	v_mfma_f32_16x16x32_bf16 v[44:47], v[142:145], v[226:229], v[44:47]
	v_mfma_f32_16x16x32_bf16 v[40:43], v[150:153], v[226:229], v[40:43]
	v_mfma_f32_16x16x32_bf16 v[36:39], v[142:145], v[234:237], v[36:39]
	v_mfma_f32_16x16x32_bf16 v[32:35], v[150:153], v[234:237], v[32:35]
	v_mfma_f32_16x16x32_bf16 v[28:31], v[154:157], v[188:191], v[28:31]
	v_mfma_f32_16x16x32_bf16 v[24:27], v[176:179], v[188:191], v[24:27]
	v_mfma_f32_16x16x32_bf16 v[20:23], v[154:157], v[214:217], v[20:23]
	v_mfma_f32_16x16x32_bf16 v[16:19], v[176:179], v[214:217], v[16:19]
	v_mfma_f32_16x16x32_bf16 v[12:15], v[154:157], v[222:225], v[12:15]
	v_mfma_f32_16x16x32_bf16 v[8:11], v[176:179], v[222:225], v[8:11]
	v_mfma_f32_16x16x32_bf16 v[4:7], v[154:157], v[230:233], v[4:7]
	v_mfma_f32_16x16x32_bf16 v[0:3], v[176:179], v[230:233], v[0:3]
	v_mfma_f32_16x16x32_bf16 v[28:31], v[172:175], v[192:195], v[28:31]
	v_mfma_f32_16x16x32_bf16 v[24:27], v[180:183], v[192:195], v[24:27]
	v_mfma_f32_16x16x32_bf16 v[20:23], v[172:175], v[218:221], v[20:23]
	v_mfma_f32_16x16x32_bf16 v[16:19], v[180:183], v[218:221], v[16:19]
	v_mfma_f32_16x16x32_bf16 v[12:15], v[172:175], v[226:229], v[12:15]
	v_mfma_f32_16x16x32_bf16 v[8:11], v[180:183], v[226:229], v[8:11]
	v_mfma_f32_16x16x32_bf16 v[4:7], v[172:175], v[234:237], v[4:7]
	v_mfma_f32_16x16x32_bf16 v[0:3], v[180:183], v[234:237], v[0:3]
	s_setprio 0
	s_barrier
	s_add_i32 s6, 0, 0x18000
	s_add_i32 s7, 0, 0x1c000
	v_add_u32_e32 v150, s6, v184
	v_add_u32_e32 v180, s7, v184
	ds_read_b128 v[138:141], v150
	ds_read_b128 v[142:145], v150 offset:1024
	ds_read_b128 v[146:149], v150 offset:2048
	ds_read_b128 v[150:153], v150 offset:3072
	ds_read_b128 v[154:157], v180
	ds_read_b128 v[172:175], v180 offset:1024
	ds_read_b128 v[176:179], v180 offset:2048
	ds_read_b128 v[180:183], v180 offset:3072
	s_add_u32 s4, s68, 0x60000
	s_addc_u32 s5, s69, 0
	s_mov_b32 m0, s27
	v_lshl_add_u64 v[242:243], s[4:5], 0, v[132:133]
	ds_read_b128 v[188:191], v186 offset:32768
	ds_read_b128 v[192:195], v186 offset:33792
	ds_read_b128 v[214:217], v186 offset:34816
	ds_read_b128 v[218:221], v186 offset:35840
	ds_read_b128 v[222:225], v186 offset:36864
	ds_read_b128 v[226:229], v186 offset:37888
	ds_read_b128 v[230:233], v186 offset:38912
	ds_read_b128 v[234:237], v186 offset:39936
	global_load_lds_dwordx4 v[242:243], off
	v_lshl_add_u64 v[242:243], s[4:5], 0, v[130:131]
	s_mov_b32 m0, s28
	s_nop 0
	global_load_lds_dwordx4 v[242:243], off
	s_waitcnt vmcnt(8)
	s_waitcnt lgkmcnt(0)
	s_barrier
	s_setprio 1
	s_waitcnt lgkmcnt(0)
	v_mfma_f32_16x16x32_bf16 v[124:127], v[138:141], v[188:191], v[124:127]
	v_mfma_f32_16x16x32_bf16 v[120:123], v[146:149], v[188:191], v[120:123]
	v_mfma_f32_16x16x32_bf16 v[116:119], v[138:141], v[214:217], v[116:119]
	v_mfma_f32_16x16x32_bf16 v[112:115], v[146:149], v[214:217], v[112:115]
	v_mfma_f32_16x16x32_bf16 v[108:111], v[138:141], v[222:225], v[108:111]
	v_mfma_f32_16x16x32_bf16 v[104:107], v[146:149], v[222:225], v[104:107]
	v_mfma_f32_16x16x32_bf16 v[100:103], v[138:141], v[230:233], v[100:103]
	v_mfma_f32_16x16x32_bf16 v[96:99], v[146:149], v[230:233], v[96:99]
	v_mfma_f32_16x16x32_bf16 v[124:127], v[142:145], v[192:195], v[124:127]
	v_mfma_f32_16x16x32_bf16 v[120:123], v[150:153], v[192:195], v[120:123]
	v_mfma_f32_16x16x32_bf16 v[116:119], v[142:145], v[218:221], v[116:119]
	v_mfma_f32_16x16x32_bf16 v[112:115], v[150:153], v[218:221], v[112:115]
	v_mfma_f32_16x16x32_bf16 v[108:111], v[142:145], v[226:229], v[108:111]
	v_mfma_f32_16x16x32_bf16 v[104:107], v[150:153], v[226:229], v[104:107]
	v_mfma_f32_16x16x32_bf16 v[100:103], v[142:145], v[234:237], v[100:103]
	v_mfma_f32_16x16x32_bf16 v[96:99], v[150:153], v[234:237], v[96:99]
	v_mfma_f32_16x16x32_bf16 v[92:95], v[154:157], v[188:191], v[92:95]
	v_mfma_f32_16x16x32_bf16 v[88:91], v[176:179], v[188:191], v[88:91]
	v_mfma_f32_16x16x32_bf16 v[84:87], v[154:157], v[214:217], v[84:87]
	v_mfma_f32_16x16x32_bf16 v[80:83], v[176:179], v[214:217], v[80:83]
	v_mfma_f32_16x16x32_bf16 v[76:79], v[154:157], v[222:225], v[76:79]
	v_mfma_f32_16x16x32_bf16 v[72:75], v[176:179], v[222:225], v[72:75]
	v_mfma_f32_16x16x32_bf16 v[68:71], v[154:157], v[230:233], v[68:71]
	v_mfma_f32_16x16x32_bf16 v[64:67], v[176:179], v[230:233], v[64:67]
	v_mfma_f32_16x16x32_bf16 v[92:95], v[172:175], v[192:195], v[92:95]
	v_mfma_f32_16x16x32_bf16 v[88:91], v[180:183], v[192:195], v[88:91]
	v_mfma_f32_16x16x32_bf16 v[84:87], v[172:175], v[218:221], v[84:87]
	v_mfma_f32_16x16x32_bf16 v[80:83], v[180:183], v[218:221], v[80:83]
	v_mfma_f32_16x16x32_bf16 v[76:79], v[172:175], v[226:229], v[76:79]
	v_mfma_f32_16x16x32_bf16 v[72:75], v[180:183], v[226:229], v[72:75]
	v_mfma_f32_16x16x32_bf16 v[68:71], v[172:175], v[234:237], v[68:71]
	v_mfma_f32_16x16x32_bf16 v[64:67], v[180:183], v[234:237], v[64:67]
	s_setprio 0
	s_barrier
; #define PG8_STAGE(bufoff, gbase, voff) do { _Pragma("unroll") for (int _i = 0; _i < 2; ++_i) \
;         __builtin_amdgcn_global_load_lds((const unsigned*)((const char*)(gbase) + (voff)[_i]), (LAS unsigned*)(lds + (bufoff) + ldsw + _i * 8192), 16, 0, 0); } while (0)
; #define PG8_LDA(dst, b, h) do { _Pragma("unroll") for (int m = 0; m < 4; ++m) _Pragma("unroll") for (int k = 0; k < 2; ++k) dst[m][k] = *(const LAS bf16x8*)(lds + PG8_SA(b, h) + aoff + m * 2048 + k * 1024); } while (0)
; #define PG8_WAIT_V(n) asm volatile("s_waitcnt vmcnt(" #n ")" ::: "memory")
; #define PG8_WAIT_L(n) asm volatile("s_waitcnt lgkmcnt(" #n ")" ::: "memory")
; #define PG8_BAR __builtin_amdgcn_s_barrier()
; #define PG8_SCHED __builtin_amdgcn_sched_barrier(0)
; template <class Epi>
; __device__ __forceinline__ void gemm_phase(LAS unsigned char* lds, const Gemm g, const Order& S, const Epi& E) {
;     ...
;             PG8_LDA(At, 1, 1); PG8_STAGE(PG8_SB(1, 0), b3, voffB); PG8_STAGE(PG8_SB(1, 1), b3 + hstepB, voffB); PG8_STAGE(PG8_SA(1, 0), a3, voffA);
;             PG8_WAIT_V(8); PG8_WAIT_L(0); PG8_BAR; PG8_MMA(1, 0, At, B0); PG8_MMA(1, 1, At, B1); PG8_BAR; PG8_SCHED;
;         }
;         if constexpr (ALIGN_EPI) { if (wr == 0) PG8_BAR; }
	s_add_i32 s4, s6, s24
	v_lshl_add_u64 v[158:159], v[158:159], 0, s[62:63]
	s_mov_b32 m0, s4
	ds_read_b128 v[188:191], v186 offset:49152
	ds_read_b128 v[192:195], v186 offset:50176
	ds_read_b128 v[214:217], v186 offset:51200
	ds_read_b128 v[218:221], v186 offset:52224
	ds_read_b128 v[222:225], v186 offset:53248
	ds_read_b128 v[226:229], v186 offset:54272
	ds_read_b128 v[230:233], v186 offset:55296
	ds_read_b128 v[234:237], v186 offset:56320
	global_load_lds_dwordx4 v[158:159], off
	s_add_i32 m0, s4, 0x2000
	s_add_u32 s4, s66, 0x20080
	v_lshl_add_u64 v[158:159], v[200:201], 0, s[62:63]
	s_addc_u32 s5, s67, 0
	s_add_i32 s6, s7, s24
	global_load_lds_dwordx4 v[158:159], off
	v_lshl_add_u64 v[158:159], s[4:5], 0, v[160:161]
	s_mov_b32 m0, s6
	s_nop 0
	global_load_lds_dwordx4 v[158:159], off
	v_lshl_add_u64 v[158:159], s[4:5], 0, v[128:129]
	s_add_i32 m0, s6, 0x2000
	s_nop 0
	global_load_lds_dwordx4 v[158:159], off
	v_lshl_add_u64 v[158:159], v[238:239], 0, s[62:63]
	s_mov_b32 m0, s29
	s_nop 0
	global_load_lds_dwordx4 v[158:159], off
	v_lshl_add_u64 v[158:159], v[240:241], 0, s[62:63]
	s_mov_b32 m0, s70
	s_nop 0
	global_load_lds_dwordx4 v[158:159], off
	s_waitcnt vmcnt(8)
	s_waitcnt lgkmcnt(0)
	s_barrier
	s_setprio 1
	s_waitcnt lgkmcnt(0)
	v_mfma_f32_16x16x32_bf16 v[60:63], v[138:141], v[188:191], v[60:63]
	v_mfma_f32_16x16x32_bf16 v[56:59], v[146:149], v[188:191], v[56:59]
	v_mfma_f32_16x16x32_bf16 v[52:55], v[138:141], v[214:217], v[52:55]
	v_mfma_f32_16x16x32_bf16 v[48:51], v[146:149], v[214:217], v[48:51]
	v_mfma_f32_16x16x32_bf16 v[44:47], v[138:141], v[222:225], v[44:47]
	v_mfma_f32_16x16x32_bf16 v[40:43], v[146:149], v[222:225], v[40:43]
	v_mfma_f32_16x16x32_bf16 v[36:39], v[138:141], v[230:233], v[36:39]
	v_mfma_f32_16x16x32_bf16 v[32:35], v[146:149], v[230:233], v[32:35]
	v_mfma_f32_16x16x32_bf16 v[60:63], v[142:145], v[192:195], v[60:63]
	v_mfma_f32_16x16x32_bf16 v[56:59], v[150:153], v[192:195], v[56:59]
	v_mfma_f32_16x16x32_bf16 v[52:55], v[142:145], v[218:221], v[52:55]
	v_mfma_f32_16x16x32_bf16 v[48:51], v[150:153], v[218:221], v[48:51]
	v_mfma_f32_16x16x32_bf16 v[44:47], v[142:145], v[226:229], v[44:47]
	v_mfma_f32_16x16x32_bf16 v[40:43], v[150:153], v[226:229], v[40:43]
	v_mfma_f32_16x16x32_bf16 v[36:39], v[142:145], v[234:237], v[36:39]
	v_mfma_f32_16x16x32_bf16 v[32:35], v[150:153], v[234:237], v[32:35]
	v_mfma_f32_16x16x32_bf16 v[28:31], v[154:157], v[188:191], v[28:31]
	v_mfma_f32_16x16x32_bf16 v[24:27], v[176:179], v[188:191], v[24:27]
	v_mfma_f32_16x16x32_bf16 v[20:23], v[154:157], v[214:217], v[20:23]
	v_mfma_f32_16x16x32_bf16 v[16:19], v[176:179], v[214:217], v[16:19]
	v_mfma_f32_16x16x32_bf16 v[12:15], v[154:157], v[222:225], v[12:15]
	v_mfma_f32_16x16x32_bf16 v[8:11], v[176:179], v[222:225], v[8:11]
	v_mfma_f32_16x16x32_bf16 v[4:7], v[154:157], v[230:233], v[4:7]
	v_mfma_f32_16x16x32_bf16 v[0:3], v[176:179], v[230:233], v[0:3]
	v_mfma_f32_16x16x32_bf16 v[28:31], v[172:175], v[192:195], v[28:31]
	v_mfma_f32_16x16x32_bf16 v[24:27], v[180:183], v[192:195], v[24:27]
	v_mfma_f32_16x16x32_bf16 v[20:23], v[172:175], v[218:221], v[20:23]
	v_mfma_f32_16x16x32_bf16 v[16:19], v[180:183], v[218:221], v[16:19]
	v_mfma_f32_16x16x32_bf16 v[12:15], v[172:175], v[226:229], v[12:15]
	v_mfma_f32_16x16x32_bf16 v[8:11], v[180:183], v[226:229], v[8:11]
	v_mfma_f32_16x16x32_bf16 v[4:7], v[172:175], v[234:237], v[4:7]
	v_mfma_f32_16x16x32_bf16 v[0:3], v[180:183], v[234:237], v[0:3]
	s_setprio 0
	s_barrier
	s_add_i32 s47, s47, 2
	s_add_u32 s43, s43, 0x100
	s_addc_u32 s45, s45, 0
	s_cmp_gt_u32 s47, 5
	s_mov_b64 s[64:65], s[40:41]
	s_cbranch_scc0 .LBB0_281
	s_and_b64 vcc, exec, s[12:13]
	s_cbranch_vccz .LBB0_284
	s_barrier

; #define PG8_STAGE(bufoff, gbase, voff) do { _Pragma("unroll") for (int _i = 0; _i < 2; ++_i) \
;         __builtin_amdgcn_global_load_lds((const unsigned*)((const char*)(gbase) + (voff)[_i]), (LAS unsigned*)(lds + (bufoff) + ldsw + _i * 8192), 16, 0, 0); } while (0)
; #define PG8_LDA(dst, b, h) do { _Pragma("unroll") for (int m = 0; m < 4; ++m) _Pragma("unroll") for (int k = 0; k < 2; ++k) dst[m][k] = *(const LAS bf16x8*)(lds + PG8_SA(b, h) + aoff + m * 2048 + k * 1024); } while (0)
; #define PG8_LDB(dst, b, h) do { _Pragma("unroll") for (int n = 0; n < 2; ++n) _Pragma("unroll") for (int k = 0; k < 2; ++k) dst[n][k] = *(const LAS bf16x8*)(lds + PG8_SB(b, h) + boff + n * 2048 + k * 1024); } while (0)
; #define PG8_WAIT_V(n) asm volatile("s_waitcnt vmcnt(" #n ")" ::: "memory")
; #define PG8_WAIT_L(n) asm volatile("s_waitcnt lgkmcnt(" #n ")" ::: "memory")
; #define PG8_BAR __builtin_amdgcn_s_barrier()
; #define PG8_SCHED __builtin_amdgcn_sched_barrier(0)
; template <class Epi>
; __device__ __forceinline__ void gemm_phase(LAS unsigned char* lds, const Gemm g, const Order& S, const Epi& E) {
;     ...
;         for (int t = 0; t < nt; t += 2) {
;             const bool last = (t == nt - 2);
;             const char* a1 = cA + (size_t)(t + 1) * kstep;
;             const char* a2 = last ? nA : cA + (size_t)(t + 2) * kstep; const char* b2 = last ? nB : cB + (size_t)(t + 2) * kstep;
;             const char* a3 = a2 + kstep; const char* b3 = b2 + kstep;
;             PG8_LDB(B0, 0, 0); PG8_LDB(B1, 0, 1); PG8_SCHED; PG8_LDA(At, 0, 0); PG8_STAGE(PG8_SA(1, 1), a1 + hstepA, voffA);
;             PG8_WAIT_V(8); PG8_WAIT_L(0); PG8_BAR; PG8_MMA(0, 0, At, B0); PG8_MMA(0, 1, At, B1); PG8_BAR; PG8_SCHED;
;             PG8_LDA(At, 0, 1); PG8_STAGE(PG8_SB(0, 0), b2, voffB); PG8_STAGE(PG8_SB(0, 1), b2 + hstepB, voffB); PG8_STAGE(PG8_SA(0, 0), a2, voffA);
;             PG8_WAIT_V(8); PG8_WAIT_L(0); PG8_BAR; PG8_MMA(1, 0, At, B0); PG8_MMA(1, 1, At, B1); PG8_BAR; PG8_SCHED;
.LBB0_396:
	s_add_u32 s4, s50, 0xfffc0080
	s_addc_u32 s5, s51, -1
	s_add_i32 s36, 0, 0x10000
	s_cmp_eq_u32 s71, 12
	s_cselect_b32 s67, s34, s5
	s_cselect_b32 s66, s35, s4
	v_add_u32_e32 v138, s36, v141
	s_cselect_b32 s65, s43, s70
	s_cselect_b32 s64, s45, s69
	s_add_i32 s4, 0, 0x14000
	ds_read_b128 v[144:147], v138
	ds_read_b128 v[148:151], v138 offset:1024
	ds_read_b128 v[152:155], v138 offset:2048
	ds_read_b128 v[156:159], v138 offset:3072
	v_add_u32_e32 v138, s4, v141
	ds_read_b128 v[172:175], v138
	ds_read_b128 v[176:179], v138 offset:1024
	ds_read_b128 v[180:183], v138 offset:2048
	ds_read_b128 v[184:187], v138 offset:3072
	v_lshl_add_u64 v[138:139], s[50:51], 0, v[134:135]
	s_add_i32 m0, s24, 0xc000
	ds_read_b128 v[188:191], v143
	ds_read_b128 v[192:195], v143 offset:1024
	ds_read_b128 v[214:217], v143 offset:2048
	ds_read_b128 v[218:221], v143 offset:3072
	ds_read_b128 v[222:225], v143 offset:4096
	ds_read_b128 v[226:229], v143 offset:5120
	ds_read_b128 v[230:233], v143 offset:6144
	ds_read_b128 v[234:237], v143 offset:7168
	global_load_lds_dwordx4 v[138:139], off
	v_lshl_add_u64 v[138:139], s[50:51], 0, v[136:137]
	s_add_i32 m0, s24, 0xe000
	s_nop 0
	global_load_lds_dwordx4 v[138:139], off
	s_waitcnt vmcnt(8)
	s_waitcnt lgkmcnt(0)
	s_barrier
	s_setprio 1
	s_waitcnt lgkmcnt(0)
	v_mfma_f32_16x16x32_f16 v[124:127], v[144:147], v[188:191], v[124:127]
	v_mfma_f32_16x16x32_f16 v[112:115], v[152:155], v[188:191], v[112:115]
	v_mfma_f32_16x16x32_f16 v[108:111], v[144:147], v[214:217], v[108:111]
	v_mfma_f32_16x16x32_f16 v[96:99], v[152:155], v[214:217], v[96:99]
	v_mfma_f32_16x16x32_f16 v[92:95], v[144:147], v[222:225], v[92:95]
	v_mfma_f32_16x16x32_f16 v[80:83], v[152:155], v[222:225], v[80:83]
	v_mfma_f32_16x16x32_f16 v[76:79], v[144:147], v[230:233], v[76:79]
	v_mfma_f32_16x16x32_f16 v[64:67], v[152:155], v[230:233], v[64:67]
	v_mfma_f32_16x16x32_f16 v[124:127], v[148:151], v[192:195], v[124:127]
	v_mfma_f32_16x16x32_f16 v[112:115], v[156:159], v[192:195], v[112:115]
	v_mfma_f32_16x16x32_f16 v[108:111], v[148:151], v[218:221], v[108:111]
	v_mfma_f32_16x16x32_f16 v[96:99], v[156:159], v[218:221], v[96:99]
	v_mfma_f32_16x16x32_f16 v[92:95], v[148:151], v[226:229], v[92:95]
	v_mfma_f32_16x16x32_f16 v[80:83], v[156:159], v[226:229], v[80:83]
	v_mfma_f32_16x16x32_f16 v[76:79], v[148:151], v[234:237], v[76:79]
	v_mfma_f32_16x16x32_f16 v[64:67], v[156:159], v[234:237], v[64:67]
	v_mfma_f32_16x16x32_f16 v[120:123], v[172:175], v[188:191], v[120:123]
	v_mfma_f32_16x16x32_f16 v[116:119], v[180:183], v[188:191], v[116:119]
	v_mfma_f32_16x16x32_f16 v[104:107], v[172:175], v[214:217], v[104:107]
	v_mfma_f32_16x16x32_f16 v[100:103], v[180:183], v[214:217], v[100:103]
	v_mfma_f32_16x16x32_f16 v[88:91], v[172:175], v[222:225], v[88:91]
	v_mfma_f32_16x16x32_f16 v[84:87], v[180:183], v[222:225], v[84:87]
	v_mfma_f32_16x16x32_f16 v[72:75], v[172:175], v[230:233], v[72:75]
	v_mfma_f32_16x16x32_f16 v[68:71], v[180:183], v[230:233], v[68:71]
	v_mfma_f32_16x16x32_f16 v[120:123], v[176:179], v[192:195], v[120:123]
	v_mfma_f32_16x16x32_f16 v[116:119], v[184:187], v[192:195], v[116:119]
	v_mfma_f32_16x16x32_f16 v[104:107], v[176:179], v[218:221], v[104:107]
	v_mfma_f32_16x16x32_f16 v[100:103], v[184:187], v[218:221], v[100:103]
	v_mfma_f32_16x16x32_f16 v[88:91], v[176:179], v[226:229], v[88:91]
	v_mfma_f32_16x16x32_f16 v[84:87], v[184:187], v[226:229], v[84:87]
	v_mfma_f32_16x16x32_f16 v[72:75], v[176:179], v[234:237], v[72:75]
	v_mfma_f32_16x16x32_f16 v[68:71], v[184:187], v[234:237], v[68:71]
	s_setprio 0
	s_barrier
	s_add_i32 s5, s36, s23
	v_lshl_add_u64 v[138:139], s[64:65], 0, v[160:161]
	s_mov_b32 m0, s5
	ds_read_b128 v[188:191], v143 offset:16384
	ds_read_b128 v[192:195], v143 offset:17408
	ds_read_b128 v[214:217], v143 offset:18432
	ds_read_b128 v[218:221], v143 offset:19456
	ds_read_b128 v[222:225], v143 offset:20480
	ds_read_b128 v[226:229], v143 offset:21504
	ds_read_b128 v[230:233], v143 offset:22528
	ds_read_b128 v[234:237], v143 offset:23552
	global_load_lds_dwordx4 v[138:139], off
	s_add_i32 m0, s5, 0x2000
	s_add_u32 s36, s64, 0x40000
	v_lshl_add_u64 v[238:239], s[64:65], 0, v[128:129]
	s_addc_u32 s37, s65, 0
	s_add_i32 s4, s4, s23
	global_load_lds_dwordx4 v[238:239], off
	v_lshl_add_u64 v[240:241], s[36:37], 0, v[160:161]
	s_mov_b32 m0, s4
	v_lshl_add_u64 v[242:243], s[66:67], 0, v[130:131]
	global_load_lds_dwordx4 v[240:241], off
	v_lshl_add_u64 v[240:241], s[36:37], 0, v[128:129]
	s_add_i32 m0, s4, 0x2000
	s_nop 0
	global_load_lds_dwordx4 v[240:241], off
	v_lshl_add_u64 v[240:241], s[66:67], 0, v[132:133]
	s_mov_b32 m0, s24
	s_nop 0
	global_load_lds_dwordx4 v[240:241], off
	s_mov_b32 m0, s25
	s_nop 0
	global_load_lds_dwordx4 v[242:243], off
	s_waitcnt vmcnt(8)
	s_waitcnt lgkmcnt(0)
	s_barrier
; #define PG8_STAGE(bufoff, gbase, voff) do { _Pragma("unroll") for (int _i = 0; _i < 2; ++_i) \
;         __builtin_amdgcn_global_load_lds((const unsigned*)((const char*)(gbase) + (voff)[_i]), (LAS unsigned*)(lds + (bufoff) + ldsw + _i * 8192), 16, 0, 0); } while (0)
; #define PG8_LDA(dst, b, h) do { _Pragma("unroll") for (int m = 0; m < 4; ++m) _Pragma("unroll") for (int k = 0; k < 2; ++k) dst[m][k] = *(const LAS bf16x8*)(lds + PG8_SA(b, h) + aoff + m * 2048 + k * 1024); } while (0)
; #define PG8_LDB(dst, b, h) do { _Pragma("unroll") for (int n = 0; n < 2; ++n) _Pragma("unroll") for (int k = 0; k < 2; ++k) dst[n][k] = *(const LAS bf16x8*)(lds + PG8_SB(b, h) + boff + n * 2048 + k * 1024); } while (0)
; #define PG8_WAIT_V(n) asm volatile("s_waitcnt vmcnt(" #n ")" ::: "memory")
; #define PG8_WAIT_L(n) asm volatile("s_waitcnt lgkmcnt(" #n ")" ::: "memory")
; #define PG8_BAR __builtin_amdgcn_s_barrier()
; #define PG8_SCHED __builtin_amdgcn_sched_barrier(0)
; template <class Epi>
; __device__ __forceinline__ void gemm_phase(LAS unsigned char* lds, const Gemm g, const Order& S, const Epi& E) {
;     ...
;             PG8_WAIT_V(8); PG8_WAIT_L(0); PG8_BAR; PG8_MMA(1, 0, At, B0); PG8_MMA(1, 1, At, B1); PG8_BAR; PG8_SCHED;
;             PG8_LDB(B0, 1, 0); PG8_LDB(B1, 1, 1); PG8_SCHED; PG8_LDA(At, 1, 0); PG8_STAGE(PG8_SA(0, 1), a2 + hstepA, voffA);
;             PG8_WAIT_V(8); PG8_WAIT_L(0); PG8_BAR; PG8_MMA(0, 0, At, B0); PG8_MMA(0, 1, At, B1); PG8_BAR; PG8_SCHED;
	s_setprio 1
	s_waitcnt lgkmcnt(0)
	v_mfma_f32_16x16x32_f16 v[60:63], v[144:147], v[188:191], v[60:63]
	v_mfma_f32_16x16x32_f16 v[48:51], v[152:155], v[188:191], v[48:51]
	v_mfma_f32_16x16x32_f16 v[44:47], v[144:147], v[214:217], v[44:47]
	v_mfma_f32_16x16x32_f16 v[32:35], v[152:155], v[214:217], v[32:35]
	v_mfma_f32_16x16x32_f16 v[28:31], v[144:147], v[222:225], v[28:31]
	v_mfma_f32_16x16x32_f16 v[16:19], v[152:155], v[222:225], v[16:19]
	v_mfma_f32_16x16x32_f16 v[12:15], v[144:147], v[230:233], v[12:15]
	v_mfma_f32_16x16x32_f16 v[0:3], v[152:155], v[230:233], v[0:3]
	v_mfma_f32_16x16x32_f16 v[60:63], v[148:151], v[192:195], v[60:63]
	v_mfma_f32_16x16x32_f16 v[48:51], v[156:159], v[192:195], v[48:51]
	v_mfma_f32_16x16x32_f16 v[44:47], v[148:151], v[218:221], v[44:47]
	v_mfma_f32_16x16x32_f16 v[32:35], v[156:159], v[218:221], v[32:35]
	v_mfma_f32_16x16x32_f16 v[28:31], v[148:151], v[226:229], v[28:31]
	v_mfma_f32_16x16x32_f16 v[16:19], v[156:159], v[226:229], v[16:19]
	v_mfma_f32_16x16x32_f16 v[12:15], v[148:151], v[234:237], v[12:15]
	v_mfma_f32_16x16x32_f16 v[0:3], v[156:159], v[234:237], v[0:3]
	v_mfma_f32_16x16x32_f16 v[56:59], v[172:175], v[188:191], v[56:59]
	v_mfma_f32_16x16x32_f16 v[52:55], v[180:183], v[188:191], v[52:55]
	v_mfma_f32_16x16x32_f16 v[40:43], v[172:175], v[214:217], v[40:43]
	v_mfma_f32_16x16x32_f16 v[36:39], v[180:183], v[214:217], v[36:39]
	v_mfma_f32_16x16x32_f16 v[24:27], v[172:175], v[222:225], v[24:27]
	v_mfma_f32_16x16x32_f16 v[20:23], v[180:183], v[222:225], v[20:23]
	v_mfma_f32_16x16x32_f16 v[8:11], v[172:175], v[230:233], v[8:11]
	v_mfma_f32_16x16x32_f16 v[4:7], v[180:183], v[230:233], v[4:7]
	v_mfma_f32_16x16x32_f16 v[56:59], v[176:179], v[192:195], v[56:59]
	v_mfma_f32_16x16x32_f16 v[52:55], v[184:187], v[192:195], v[52:55]
	v_mfma_f32_16x16x32_f16 v[40:43], v[176:179], v[218:221], v[40:43]
	v_mfma_f32_16x16x32_f16 v[36:39], v[184:187], v[218:221], v[36:39]
	v_mfma_f32_16x16x32_f16 v[24:27], v[176:179], v[226:229], v[24:27]
	v_mfma_f32_16x16x32_f16 v[20:23], v[184:187], v[226:229], v[20:23]
	v_mfma_f32_16x16x32_f16 v[8:11], v[176:179], v[234:237], v[8:11]
	v_mfma_f32_16x16x32_f16 v[4:7], v[184:187], v[234:237], v[4:7]
	s_setprio 0
	s_barrier
	s_add_i32 s4, 0, 0x18000
	s_add_i32 s5, 0, 0x1c000
	v_add_u32_e32 v156, s4, v141
	v_add_u32_e32 v171, s5, v141
	ds_read_b128 v[144:147], v156
	ds_read_b128 v[148:151], v156 offset:1024
	ds_read_b128 v[152:155], v156 offset:2048
	ds_read_b128 v[156:159], v156 offset:3072
	ds_read_b128 v[172:175], v171
	ds_read_b128 v[176:179], v171 offset:1024
	ds_read_b128 v[180:183], v171 offset:2048
	ds_read_b128 v[184:187], v171 offset:3072
	s_add_u32 s36, s66, 0x40000
	s_addc_u32 s37, s67, 0
	s_mov_b32 m0, s26
	v_lshl_add_u64 v[244:245], s[36:37], 0, v[132:133]
	ds_read_b128 v[188:191], v143 offset:32768
	ds_read_b128 v[192:195], v143 offset:33792
	ds_read_b128 v[214:217], v143 offset:34816
	ds_read_b128 v[218:221], v143 offset:35840
	ds_read_b128 v[222:225], v143 offset:36864
	ds_read_b128 v[226:229], v143 offset:37888
	ds_read_b128 v[230:233], v143 offset:38912
	ds_read_b128 v[234:237], v143 offset:39936
	global_load_lds_dwordx4 v[244:245], off
	v_lshl_add_u64 v[244:245], s[36:37], 0, v[130:131]
	s_mov_b32 m0, s27
	s_nop 0
	global_load_lds_dwordx4 v[244:245], off
	s_waitcnt vmcnt(8)
	s_waitcnt lgkmcnt(0)
	s_barrier
	s_setprio 1
	s_waitcnt lgkmcnt(0)
	v_mfma_f32_16x16x32_f16 v[124:127], v[144:147], v[188:191], v[124:127]
	v_mfma_f32_16x16x32_f16 v[112:115], v[152:155], v[188:191], v[112:115]
	v_mfma_f32_16x16x32_f16 v[108:111], v[144:147], v[214:217], v[108:111]
	v_mfma_f32_16x16x32_f16 v[96:99], v[152:155], v[214:217], v[96:99]
	v_mfma_f32_16x16x32_f16 v[92:95], v[144:147], v[222:225], v[92:95]
	v_mfma_f32_16x16x32_f16 v[80:83], v[152:155], v[222:225], v[80:83]
	v_mfma_f32_16x16x32_f16 v[76:79], v[144:147], v[230:233], v[76:79]
	v_mfma_f32_16x16x32_f16 v[64:67], v[152:155], v[230:233], v[64:67]
	v_mfma_f32_16x16x32_f16 v[124:127], v[148:151], v[192:195], v[124:127]
	v_mfma_f32_16x16x32_f16 v[112:115], v[156:159], v[192:195], v[112:115]
	v_mfma_f32_16x16x32_f16 v[108:111], v[148:151], v[218:221], v[108:111]
	v_mfma_f32_16x16x32_f16 v[96:99], v[156:159], v[218:221], v[96:99]
	v_mfma_f32_16x16x32_f16 v[92:95], v[148:151], v[226:229], v[92:95]
	v_mfma_f32_16x16x32_f16 v[80:83], v[156:159], v[226:229], v[80:83]
	v_mfma_f32_16x16x32_f16 v[76:79], v[148:151], v[234:237], v[76:79]
	v_mfma_f32_16x16x32_f16 v[64:67], v[156:159], v[234:237], v[64:67]
	v_mfma_f32_16x16x32_f16 v[120:123], v[172:175], v[188:191], v[120:123]
	v_mfma_f32_16x16x32_f16 v[116:119], v[180:183], v[188:191], v[116:119]
	v_mfma_f32_16x16x32_f16 v[104:107], v[172:175], v[214:217], v[104:107]
	v_mfma_f32_16x16x32_f16 v[100:103], v[180:183], v[214:217], v[100:103]
	v_mfma_f32_16x16x32_f16 v[88:91], v[172:175], v[222:225], v[88:91]
	v_mfma_f32_16x16x32_f16 v[84:87], v[180:183], v[222:225], v[84:87]
	v_mfma_f32_16x16x32_f16 v[72:75], v[172:175], v[230:233], v[72:75]
	v_mfma_f32_16x16x32_f16 v[68:71], v[180:183], v[230:233], v[68:71]
	v_mfma_f32_16x16x32_f16 v[120:123], v[176:179], v[192:195], v[120:123]
	v_mfma_f32_16x16x32_f16 v[116:119], v[184:187], v[192:195], v[116:119]
	v_mfma_f32_16x16x32_f16 v[104:107], v[176:179], v[218:221], v[104:107]
	v_mfma_f32_16x16x32_f16 v[100:103], v[184:187], v[218:221], v[100:103]
	v_mfma_f32_16x16x32_f16 v[88:91], v[176:179], v[226:229], v[88:91]
	v_mfma_f32_16x16x32_f16 v[84:87], v[184:187], v[226:229], v[84:87]
	v_mfma_f32_16x16x32_f16 v[72:75], v[176:179], v[234:237], v[72:75]
	v_mfma_f32_16x16x32_f16 v[68:71], v[184:187], v[234:237], v[68:71]
	s_setprio 0
	s_barrier
; #define PG8_STAGE(bufoff, gbase, voff) do { _Pragma("unroll") for (int _i = 0; _i < 2; ++_i) \
;         __builtin_amdgcn_global_load_lds((const unsigned*)((const char*)(gbase) + (voff)[_i]), (LAS unsigned*)(lds + (bufoff) + ldsw + _i * 8192), 16, 0, 0); } while (0)
; #define PG8_LDA(dst, b, h) do { _Pragma("unroll") for (int m = 0; m < 4; ++m) _Pragma("unroll") for (int k = 0; k < 2; ++k) dst[m][k] = *(const LAS bf16x8*)(lds + PG8_SA(b, h) + aoff + m * 2048 + k * 1024); } while (0)
; #define PG8_WAIT_V(n) asm volatile("s_waitcnt vmcnt(" #n ")" ::: "memory")
; #define PG8_WAIT_L(n) asm volatile("s_waitcnt lgkmcnt(" #n ")" ::: "memory")
; #define PG8_BAR __builtin_amdgcn_s_barrier()
; #define PG8_SCHED __builtin_amdgcn_sched_barrier(0)
; template <class Epi>
; __device__ __forceinline__ void gemm_phase(LAS unsigned char* lds, const Gemm g, const Order& S, const Epi& E) {
;     ...
;             PG8_LDA(At, 1, 1); PG8_STAGE(PG8_SB(1, 0), b3, voffB); PG8_STAGE(PG8_SB(1, 1), b3 + hstepB, voffB); PG8_STAGE(PG8_SA(1, 0), a3, voffA);
;             PG8_WAIT_V(8); PG8_WAIT_L(0); PG8_BAR; PG8_MMA(1, 0, At, B0); PG8_MMA(1, 1, At, B1); PG8_BAR; PG8_SCHED;
;         }
;         if constexpr (ALIGN_EPI) { if (wr == 0) PG8_BAR; }
	s_add_i32 s4, s4, s23
	v_lshl_add_u64 v[138:139], v[138:139], 0, s[62:63]
	s_mov_b32 m0, s4
	ds_read_b128 v[188:191], v143 offset:49152
	ds_read_b128 v[192:195], v143 offset:50176
	ds_read_b128 v[214:217], v143 offset:51200
	ds_read_b128 v[218:221], v143 offset:52224
	ds_read_b128 v[222:225], v143 offset:53248
	ds_read_b128 v[226:229], v143 offset:54272
	ds_read_b128 v[230:233], v143 offset:55296
	ds_read_b128 v[234:237], v143 offset:56320
	global_load_lds_dwordx4 v[138:139], off
	s_add_i32 m0, s4, 0x2000
	s_add_u32 s36, s64, 0x40080
	v_lshl_add_u64 v[138:139], v[238:239], 0, s[62:63]
	s_addc_u32 s37, s65, 0
	s_add_i32 s4, s5, s23
	global_load_lds_dwordx4 v[138:139], off
	v_lshl_add_u64 v[138:139], s[36:37], 0, v[160:161]
	s_mov_b32 m0, s4
	s_nop 0
	global_load_lds_dwordx4 v[138:139], off
	v_lshl_add_u64 v[138:139], s[36:37], 0, v[128:129]
	s_add_i32 m0, s4, 0x2000
	s_nop 0
	global_load_lds_dwordx4 v[138:139], off
	v_lshl_add_u64 v[138:139], v[240:241], 0, s[62:63]
	s_mov_b32 m0, s28
	s_nop 0
	global_load_lds_dwordx4 v[138:139], off
	v_lshl_add_u64 v[138:139], v[242:243], 0, s[62:63]
	s_mov_b32 m0, s29
	s_nop 0
	global_load_lds_dwordx4 v[138:139], off
	s_waitcnt vmcnt(8)
	s_waitcnt lgkmcnt(0)
	s_barrier
	s_setprio 1
	s_waitcnt lgkmcnt(0)
	v_mfma_f32_16x16x32_f16 v[60:63], v[144:147], v[188:191], v[60:63]
	v_mfma_f32_16x16x32_f16 v[48:51], v[152:155], v[188:191], v[48:51]
	v_mfma_f32_16x16x32_f16 v[44:47], v[144:147], v[214:217], v[44:47]
	v_mfma_f32_16x16x32_f16 v[32:35], v[152:155], v[214:217], v[32:35]
	v_mfma_f32_16x16x32_f16 v[28:31], v[144:147], v[222:225], v[28:31]
	v_mfma_f32_16x16x32_f16 v[16:19], v[152:155], v[222:225], v[16:19]
	v_mfma_f32_16x16x32_f16 v[12:15], v[144:147], v[230:233], v[12:15]
	v_mfma_f32_16x16x32_f16 v[0:3], v[152:155], v[230:233], v[0:3]
	v_mfma_f32_16x16x32_f16 v[60:63], v[148:151], v[192:195], v[60:63]
	v_mfma_f32_16x16x32_f16 v[48:51], v[156:159], v[192:195], v[48:51]
	v_mfma_f32_16x16x32_f16 v[44:47], v[148:151], v[218:221], v[44:47]
	v_mfma_f32_16x16x32_f16 v[32:35], v[156:159], v[218:221], v[32:35]
	v_mfma_f32_16x16x32_f16 v[28:31], v[148:151], v[226:229], v[28:31]
	v_mfma_f32_16x16x32_f16 v[16:19], v[156:159], v[226:229], v[16:19]
	v_mfma_f32_16x16x32_f16 v[12:15], v[148:151], v[234:237], v[12:15]
	v_mfma_f32_16x16x32_f16 v[0:3], v[156:159], v[234:237], v[0:3]
	v_mfma_f32_16x16x32_f16 v[56:59], v[172:175], v[188:191], v[56:59]
	v_mfma_f32_16x16x32_f16 v[52:55], v[180:183], v[188:191], v[52:55]
	v_mfma_f32_16x16x32_f16 v[40:43], v[172:175], v[214:217], v[40:43]
	v_mfma_f32_16x16x32_f16 v[36:39], v[180:183], v[214:217], v[36:39]
	v_mfma_f32_16x16x32_f16 v[24:27], v[172:175], v[222:225], v[24:27]
	v_mfma_f32_16x16x32_f16 v[20:23], v[180:183], v[222:225], v[20:23]
	v_mfma_f32_16x16x32_f16 v[8:11], v[172:175], v[230:233], v[8:11]
	v_mfma_f32_16x16x32_f16 v[4:7], v[180:183], v[230:233], v[4:7]
	v_mfma_f32_16x16x32_f16 v[56:59], v[176:179], v[192:195], v[56:59]
	v_mfma_f32_16x16x32_f16 v[52:55], v[184:187], v[192:195], v[52:55]
	v_mfma_f32_16x16x32_f16 v[40:43], v[176:179], v[218:221], v[40:43]
	v_mfma_f32_16x16x32_f16 v[36:39], v[184:187], v[218:221], v[36:39]
	v_mfma_f32_16x16x32_f16 v[24:27], v[176:179], v[226:229], v[24:27]
	v_mfma_f32_16x16x32_f16 v[20:23], v[184:187], v[226:229], v[20:23]
	v_mfma_f32_16x16x32_f16 v[8:11], v[176:179], v[234:237], v[8:11]
	v_mfma_f32_16x16x32_f16 v[4:7], v[184:187], v[234:237], v[4:7]
	s_setprio 0
	s_barrier
	s_add_i32 s71, s71, 2
	s_add_u32 s50, s50, 0x100
	s_addc_u32 s51, s51, 0
	s_add_u32 s69, s69, 0x100
	s_addc_u32 s70, s70, 0
	s_cmp_gt_u32 s71, 13
	s_cbranch_scc0 .LBB0_396
	s_and_b64 vcc, exec, s[40:41]
	s_cbranch_vccz .LBB0_399
	s_barrier

; #define PG8_STAGE(bufoff, gbase, voff) do { _Pragma("unroll") for (int _i = 0; _i < 2; ++_i) \
;         __builtin_amdgcn_global_load_lds((const unsigned*)((const char*)(gbase) + (voff)[_i]), (LAS unsigned*)(lds + (bufoff) + ldsw + _i * 8192), 16, 0, 0); } while (0)
; #define PG8_LDA(dst, b, h) do { _Pragma("unroll") for (int m = 0; m < 4; ++m) _Pragma("unroll") for (int k = 0; k < 2; ++k) dst[m][k] = *(const LAS bf16x8*)(lds + PG8_SA(b, h) + aoff + m * 2048 + k * 1024); } while (0)
; #define PG8_LDB(dst, b, h) do { _Pragma("unroll") for (int n = 0; n < 2; ++n) _Pragma("unroll") for (int k = 0; k < 2; ++k) dst[n][k] = *(const LAS bf16x8*)(lds + PG8_SB(b, h) + boff + n * 2048 + k * 1024); } while (0)
; #define PG8_WAIT_V(n) asm volatile("s_waitcnt vmcnt(" #n ")" ::: "memory")
; #define PG8_WAIT_L(n) asm volatile("s_waitcnt lgkmcnt(" #n ")" ::: "memory")
; #define PG8_BAR __builtin_amdgcn_s_barrier()
; #define PG8_SCHED __builtin_amdgcn_sched_barrier(0)
; template <class Epi>
; __device__ __forceinline__ void gemm_phase(LAS unsigned char* lds, const Gemm g, const Order& S, const Epi& E) {
;     ...
;         for (int t = 0; t < nt; t += 2) {
;             const bool last = (t == nt - 2);
;             const char* a1 = cA + (size_t)(t + 1) * kstep;
;             const char* a2 = last ? nA : cA + (size_t)(t + 2) * kstep; const char* b2 = last ? nB : cB + (size_t)(t + 2) * kstep;
;             const char* a3 = a2 + kstep; const char* b3 = b2 + kstep;
;             PG8_LDB(B0, 0, 0); PG8_LDB(B1, 0, 1); PG8_SCHED; PG8_LDA(At, 0, 0); PG8_STAGE(PG8_SA(1, 1), a1 + hstepA, voffA);
;             PG8_WAIT_V(8); PG8_WAIT_L(0); PG8_BAR; PG8_MMA(0, 0, At, B0); PG8_MMA(0, 1, At, B1); PG8_BAR; PG8_SCHED;
;             PG8_LDA(At, 0, 1); PG8_STAGE(PG8_SB(0, 0), b2, voffB); PG8_STAGE(PG8_SB(0, 1), b2 + hstepB, voffB); PG8_STAGE(PG8_SA(0, 0), a2, voffA);
;             PG8_WAIT_V(8); PG8_WAIT_L(0); PG8_BAR; PG8_MMA(1, 0, At, B0); PG8_MMA(1, 1, At, B1); PG8_BAR; PG8_SCHED;
.LBB0_413:
	s_add_u32 s4, s48, 0xfffc0080
	s_addc_u32 s5, s49, -1
	s_add_i32 s36, 0, 0x10000
	s_cmp_eq_u32 s66, 12
	s_cselect_b32 s65, s30, s5
	s_cselect_b32 s64, s31, s4
	v_add_u32_e32 v138, s36, v141
	s_cselect_b32 s51, s34, s43
	s_cselect_b32 s50, s35, s41
	s_add_i32 s4, 0, 0x14000
	ds_read_b128 v[144:147], v138
	ds_read_b128 v[148:151], v138 offset:1024
	ds_read_b128 v[152:155], v138 offset:2048
	ds_read_b128 v[156:159], v138 offset:3072
	v_add_u32_e32 v138, s4, v141
	ds_read_b128 v[172:175], v138
	ds_read_b128 v[176:179], v138 offset:1024
	ds_read_b128 v[180:183], v138 offset:2048
	ds_read_b128 v[184:187], v138 offset:3072
	v_lshl_add_u64 v[138:139], s[48:49], 0, v[134:135]
	s_add_i32 m0, s21, 0xc000
	ds_read_b128 v[188:191], v143
	ds_read_b128 v[192:195], v143 offset:1024
	ds_read_b128 v[214:217], v143 offset:2048
	ds_read_b128 v[218:221], v143 offset:3072
	ds_read_b128 v[222:225], v143 offset:4096
	ds_read_b128 v[226:229], v143 offset:5120
	ds_read_b128 v[230:233], v143 offset:6144
	ds_read_b128 v[234:237], v143 offset:7168
	global_load_lds_dwordx4 v[138:139], off
	v_lshl_add_u64 v[138:139], s[48:49], 0, v[136:137]
	s_add_i32 m0, s21, 0xe000
	s_nop 0
	global_load_lds_dwordx4 v[138:139], off
	s_waitcnt vmcnt(8)
	s_waitcnt lgkmcnt(0)
	s_barrier
	s_setprio 1
	s_waitcnt lgkmcnt(0)
	v_mfma_f32_16x16x32_bf16 v[124:127], v[144:147], v[188:191], v[124:127]
	v_mfma_f32_16x16x32_bf16 v[120:123], v[152:155], v[188:191], v[120:123]
	v_mfma_f32_16x16x32_bf16 v[116:119], v[144:147], v[214:217], v[116:119]
	v_mfma_f32_16x16x32_bf16 v[108:111], v[152:155], v[214:217], v[108:111]
	v_mfma_f32_16x16x32_bf16 v[100:103], v[144:147], v[222:225], v[100:103]
	v_mfma_f32_16x16x32_bf16 v[92:95], v[152:155], v[222:225], v[92:95]
	v_mfma_f32_16x16x32_bf16 v[84:87], v[144:147], v[230:233], v[84:87]
	v_mfma_f32_16x16x32_bf16 v[76:79], v[152:155], v[230:233], v[76:79]
	v_mfma_f32_16x16x32_bf16 v[124:127], v[148:151], v[192:195], v[124:127]
	v_mfma_f32_16x16x32_bf16 v[120:123], v[156:159], v[192:195], v[120:123]
	v_mfma_f32_16x16x32_bf16 v[116:119], v[148:151], v[218:221], v[116:119]
	v_mfma_f32_16x16x32_bf16 v[108:111], v[156:159], v[218:221], v[108:111]
	v_mfma_f32_16x16x32_bf16 v[100:103], v[148:151], v[226:229], v[100:103]
	v_mfma_f32_16x16x32_bf16 v[92:95], v[156:159], v[226:229], v[92:95]
	v_mfma_f32_16x16x32_bf16 v[84:87], v[148:151], v[234:237], v[84:87]
	v_mfma_f32_16x16x32_bf16 v[76:79], v[156:159], v[234:237], v[76:79]
	v_mfma_f32_16x16x32_bf16 v[112:115], v[172:175], v[188:191], v[112:115]
	v_mfma_f32_16x16x32_bf16 v[104:107], v[180:183], v[188:191], v[104:107]
	v_mfma_f32_16x16x32_bf16 v[96:99], v[172:175], v[214:217], v[96:99]
	v_mfma_f32_16x16x32_bf16 v[88:91], v[180:183], v[214:217], v[88:91]
	v_mfma_f32_16x16x32_bf16 v[80:83], v[172:175], v[222:225], v[80:83]
	v_mfma_f32_16x16x32_bf16 v[72:75], v[180:183], v[222:225], v[72:75]
	v_mfma_f32_16x16x32_bf16 v[68:71], v[172:175], v[230:233], v[68:71]
	v_mfma_f32_16x16x32_bf16 v[64:67], v[180:183], v[230:233], v[64:67]
	v_mfma_f32_16x16x32_bf16 v[112:115], v[176:179], v[192:195], v[112:115]
	v_mfma_f32_16x16x32_bf16 v[104:107], v[184:187], v[192:195], v[104:107]
	v_mfma_f32_16x16x32_bf16 v[96:99], v[176:179], v[218:221], v[96:99]
	v_mfma_f32_16x16x32_bf16 v[88:91], v[184:187], v[218:221], v[88:91]
	v_mfma_f32_16x16x32_bf16 v[80:83], v[176:179], v[226:229], v[80:83]
	v_mfma_f32_16x16x32_bf16 v[72:75], v[184:187], v[226:229], v[72:75]
	v_mfma_f32_16x16x32_bf16 v[68:71], v[176:179], v[234:237], v[68:71]
	v_mfma_f32_16x16x32_bf16 v[64:67], v[184:187], v[234:237], v[64:67]
	s_setprio 0
	s_barrier
	s_add_i32 s5, s36, s1
	v_lshl_add_u64 v[138:139], s[50:51], 0, v[160:161]
	s_mov_b32 m0, s5
	ds_read_b128 v[188:191], v143 offset:16384
	ds_read_b128 v[192:195], v143 offset:17408
	ds_read_b128 v[214:217], v143 offset:18432
	ds_read_b128 v[218:221], v143 offset:19456
	ds_read_b128 v[222:225], v143 offset:20480
	ds_read_b128 v[226:229], v143 offset:21504
	ds_read_b128 v[230:233], v143 offset:22528
	ds_read_b128 v[234:237], v143 offset:23552
	global_load_lds_dwordx4 v[138:139], off
	s_add_i32 m0, s5, 0x2000
	s_add_u32 s36, s50, 0x40000
	v_lshl_add_u64 v[238:239], s[50:51], 0, v[128:129]
	s_addc_u32 s37, s51, 0
	s_add_i32 s4, s4, s1
	global_load_lds_dwordx4 v[238:239], off
	v_lshl_add_u64 v[240:241], s[36:37], 0, v[160:161]
	s_mov_b32 m0, s4
	v_lshl_add_u64 v[242:243], s[64:65], 0, v[130:131]
	global_load_lds_dwordx4 v[240:241], off
	v_lshl_add_u64 v[240:241], s[36:37], 0, v[128:129]
	s_add_i32 m0, s4, 0x2000
	s_nop 0
	global_load_lds_dwordx4 v[240:241], off
	v_lshl_add_u64 v[240:241], s[64:65], 0, v[132:133]
	s_mov_b32 m0, s21
	s_nop 0
	global_load_lds_dwordx4 v[240:241], off
	s_mov_b32 m0, s22
	s_nop 0
	global_load_lds_dwordx4 v[242:243], off
	s_waitcnt vmcnt(8)
	s_waitcnt lgkmcnt(0)
	s_barrier
; #define PG8_STAGE(bufoff, gbase, voff) do { _Pragma("unroll") for (int _i = 0; _i < 2; ++_i) \
;         __builtin_amdgcn_global_load_lds((const unsigned*)((const char*)(gbase) + (voff)[_i]), (LAS unsigned*)(lds + (bufoff) + ldsw + _i * 8192), 16, 0, 0); } while (0)
; #define PG8_LDA(dst, b, h) do { _Pragma("unroll") for (int m = 0; m < 4; ++m) _Pragma("unroll") for (int k = 0; k < 2; ++k) dst[m][k] = *(const LAS bf16x8*)(lds + PG8_SA(b, h) + aoff + m * 2048 + k * 1024); } while (0)
; #define PG8_LDB(dst, b, h) do { _Pragma("unroll") for (int n = 0; n < 2; ++n) _Pragma("unroll") for (int k = 0; k < 2; ++k) dst[n][k] = *(const LAS bf16x8*)(lds + PG8_SB(b, h) + boff + n * 2048 + k * 1024); } while (0)
; #define PG8_WAIT_V(n) asm volatile("s_waitcnt vmcnt(" #n ")" ::: "memory")
; #define PG8_WAIT_L(n) asm volatile("s_waitcnt lgkmcnt(" #n ")" ::: "memory")
; #define PG8_BAR __builtin_amdgcn_s_barrier()
; #define PG8_SCHED __builtin_amdgcn_sched_barrier(0)
; template <class Epi>
; __device__ __forceinline__ void gemm_phase(LAS unsigned char* lds, const Gemm g, const Order& S, const Epi& E) {
;     ...
;             PG8_WAIT_V(8); PG8_WAIT_L(0); PG8_BAR; PG8_MMA(1, 0, At, B0); PG8_MMA(1, 1, At, B1); PG8_BAR; PG8_SCHED;
;             PG8_LDB(B0, 1, 0); PG8_LDB(B1, 1, 1); PG8_SCHED; PG8_LDA(At, 1, 0); PG8_STAGE(PG8_SA(0, 1), a2 + hstepA, voffA);
;             PG8_WAIT_V(8); PG8_WAIT_L(0); PG8_BAR; PG8_MMA(0, 0, At, B0); PG8_MMA(0, 1, At, B1); PG8_BAR; PG8_SCHED;
	s_setprio 1
	s_waitcnt lgkmcnt(0)
	v_mfma_f32_16x16x32_bf16 v[60:63], v[144:147], v[188:191], v[60:63]
	v_mfma_f32_16x16x32_bf16 v[56:59], v[152:155], v[188:191], v[56:59]
	v_mfma_f32_16x16x32_bf16 v[52:55], v[144:147], v[214:217], v[52:55]
	v_mfma_f32_16x16x32_bf16 v[44:47], v[152:155], v[214:217], v[44:47]
	v_mfma_f32_16x16x32_bf16 v[36:39], v[144:147], v[222:225], v[36:39]
	v_mfma_f32_16x16x32_bf16 v[28:31], v[152:155], v[222:225], v[28:31]
	v_mfma_f32_16x16x32_bf16 v[20:23], v[144:147], v[230:233], v[20:23]
	v_mfma_f32_16x16x32_bf16 v[12:15], v[152:155], v[230:233], v[12:15]
	v_mfma_f32_16x16x32_bf16 v[60:63], v[148:151], v[192:195], v[60:63]
	v_mfma_f32_16x16x32_bf16 v[56:59], v[156:159], v[192:195], v[56:59]
	v_mfma_f32_16x16x32_bf16 v[52:55], v[148:151], v[218:221], v[52:55]
	v_mfma_f32_16x16x32_bf16 v[44:47], v[156:159], v[218:221], v[44:47]
	v_mfma_f32_16x16x32_bf16 v[36:39], v[148:151], v[226:229], v[36:39]
	v_mfma_f32_16x16x32_bf16 v[28:31], v[156:159], v[226:229], v[28:31]
	v_mfma_f32_16x16x32_bf16 v[20:23], v[148:151], v[234:237], v[20:23]
	v_mfma_f32_16x16x32_bf16 v[12:15], v[156:159], v[234:237], v[12:15]
	v_mfma_f32_16x16x32_bf16 v[48:51], v[172:175], v[188:191], v[48:51]
	v_mfma_f32_16x16x32_bf16 v[40:43], v[180:183], v[188:191], v[40:43]
	v_mfma_f32_16x16x32_bf16 v[32:35], v[172:175], v[214:217], v[32:35]
	v_mfma_f32_16x16x32_bf16 v[24:27], v[180:183], v[214:217], v[24:27]
	v_mfma_f32_16x16x32_bf16 v[16:19], v[172:175], v[222:225], v[16:19]
	v_mfma_f32_16x16x32_bf16 v[8:11], v[180:183], v[222:225], v[8:11]
	v_mfma_f32_16x16x32_bf16 v[4:7], v[172:175], v[230:233], v[4:7]
	v_mfma_f32_16x16x32_bf16 v[0:3], v[180:183], v[230:233], v[0:3]
	v_mfma_f32_16x16x32_bf16 v[48:51], v[176:179], v[192:195], v[48:51]
	v_mfma_f32_16x16x32_bf16 v[40:43], v[184:187], v[192:195], v[40:43]
	v_mfma_f32_16x16x32_bf16 v[32:35], v[176:179], v[218:221], v[32:35]
	v_mfma_f32_16x16x32_bf16 v[24:27], v[184:187], v[218:221], v[24:27]
	v_mfma_f32_16x16x32_bf16 v[16:19], v[176:179], v[226:229], v[16:19]
	v_mfma_f32_16x16x32_bf16 v[8:11], v[184:187], v[226:229], v[8:11]
	v_mfma_f32_16x16x32_bf16 v[4:7], v[176:179], v[234:237], v[4:7]
	v_mfma_f32_16x16x32_bf16 v[0:3], v[184:187], v[234:237], v[0:3]
	s_setprio 0
	s_barrier
	s_add_i32 s4, 0, 0x18000
	s_add_i32 s5, 0, 0x1c000
	v_add_u32_e32 v156, s4, v141
	v_add_u32_e32 v171, s5, v141
	ds_read_b128 v[144:147], v156
	ds_read_b128 v[148:151], v156 offset:1024
	ds_read_b128 v[152:155], v156 offset:2048
	ds_read_b128 v[156:159], v156 offset:3072
	ds_read_b128 v[172:175], v171
	ds_read_b128 v[176:179], v171 offset:1024
	ds_read_b128 v[180:183], v171 offset:2048
	ds_read_b128 v[184:187], v171 offset:3072
	s_add_u32 s36, s64, 0x40000
	s_addc_u32 s37, s65, 0
	s_mov_b32 m0, s23
	v_lshl_add_u64 v[244:245], s[36:37], 0, v[132:133]
	ds_read_b128 v[188:191], v143 offset:32768
	ds_read_b128 v[192:195], v143 offset:33792
	ds_read_b128 v[214:217], v143 offset:34816
	ds_read_b128 v[218:221], v143 offset:35840
	ds_read_b128 v[222:225], v143 offset:36864
	ds_read_b128 v[226:229], v143 offset:37888
	ds_read_b128 v[230:233], v143 offset:38912
	ds_read_b128 v[234:237], v143 offset:39936
	global_load_lds_dwordx4 v[244:245], off
	v_lshl_add_u64 v[244:245], s[36:37], 0, v[130:131]
	s_mov_b32 m0, s24
	s_nop 0
	global_load_lds_dwordx4 v[244:245], off
	s_waitcnt vmcnt(8)
	s_waitcnt lgkmcnt(0)
	s_barrier
	s_setprio 1
	s_waitcnt lgkmcnt(0)
	v_mfma_f32_16x16x32_bf16 v[124:127], v[144:147], v[188:191], v[124:127]
	v_mfma_f32_16x16x32_bf16 v[120:123], v[152:155], v[188:191], v[120:123]
	v_mfma_f32_16x16x32_bf16 v[116:119], v[144:147], v[214:217], v[116:119]
	v_mfma_f32_16x16x32_bf16 v[108:111], v[152:155], v[214:217], v[108:111]
	v_mfma_f32_16x16x32_bf16 v[100:103], v[144:147], v[222:225], v[100:103]
	v_mfma_f32_16x16x32_bf16 v[92:95], v[152:155], v[222:225], v[92:95]
	v_mfma_f32_16x16x32_bf16 v[84:87], v[144:147], v[230:233], v[84:87]
	v_mfma_f32_16x16x32_bf16 v[76:79], v[152:155], v[230:233], v[76:79]
	v_mfma_f32_16x16x32_bf16 v[124:127], v[148:151], v[192:195], v[124:127]
	v_mfma_f32_16x16x32_bf16 v[120:123], v[156:159], v[192:195], v[120:123]
	v_mfma_f32_16x16x32_bf16 v[116:119], v[148:151], v[218:221], v[116:119]
	v_mfma_f32_16x16x32_bf16 v[108:111], v[156:159], v[218:221], v[108:111]
	v_mfma_f32_16x16x32_bf16 v[100:103], v[148:151], v[226:229], v[100:103]
	v_mfma_f32_16x16x32_bf16 v[92:95], v[156:159], v[226:229], v[92:95]
	v_mfma_f32_16x16x32_bf16 v[84:87], v[148:151], v[234:237], v[84:87]
	v_mfma_f32_16x16x32_bf16 v[76:79], v[156:159], v[234:237], v[76:79]
	v_mfma_f32_16x16x32_bf16 v[112:115], v[172:175], v[188:191], v[112:115]
	v_mfma_f32_16x16x32_bf16 v[104:107], v[180:183], v[188:191], v[104:107]
	v_mfma_f32_16x16x32_bf16 v[96:99], v[172:175], v[214:217], v[96:99]
	v_mfma_f32_16x16x32_bf16 v[88:91], v[180:183], v[214:217], v[88:91]
	v_mfma_f32_16x16x32_bf16 v[80:83], v[172:175], v[222:225], v[80:83]
	v_mfma_f32_16x16x32_bf16 v[72:75], v[180:183], v[222:225], v[72:75]
	v_mfma_f32_16x16x32_bf16 v[68:71], v[172:175], v[230:233], v[68:71]
	v_mfma_f32_16x16x32_bf16 v[64:67], v[180:183], v[230:233], v[64:67]
	v_mfma_f32_16x16x32_bf16 v[112:115], v[176:179], v[192:195], v[112:115]
	v_mfma_f32_16x16x32_bf16 v[104:107], v[184:187], v[192:195], v[104:107]
	v_mfma_f32_16x16x32_bf16 v[96:99], v[176:179], v[218:221], v[96:99]
	v_mfma_f32_16x16x32_bf16 v[88:91], v[184:187], v[218:221], v[88:91]
	v_mfma_f32_16x16x32_bf16 v[80:83], v[176:179], v[226:229], v[80:83]
	v_mfma_f32_16x16x32_bf16 v[72:75], v[184:187], v[226:229], v[72:75]
	v_mfma_f32_16x16x32_bf16 v[68:71], v[176:179], v[234:237], v[68:71]
	v_mfma_f32_16x16x32_bf16 v[64:67], v[184:187], v[234:237], v[64:67]
	s_setprio 0
	s_barrier
; #define PG8_STAGE(bufoff, gbase, voff) do { _Pragma("unroll") for (int _i = 0; _i < 2; ++_i) \
;         __builtin_amdgcn_global_load_lds((const unsigned*)((const char*)(gbase) + (voff)[_i]), (LAS unsigned*)(lds + (bufoff) + ldsw + _i * 8192), 16, 0, 0); } while (0)
; #define PG8_LDA(dst, b, h) do { _Pragma("unroll") for (int m = 0; m < 4; ++m) _Pragma("unroll") for (int k = 0; k < 2; ++k) dst[m][k] = *(const LAS bf16x8*)(lds + PG8_SA(b, h) + aoff + m * 2048 + k * 1024); } while (0)
; #define PG8_WAIT_V(n) asm volatile("s_waitcnt vmcnt(" #n ")" ::: "memory")
; #define PG8_WAIT_L(n) asm volatile("s_waitcnt lgkmcnt(" #n ")" ::: "memory")
; #define PG8_BAR __builtin_amdgcn_s_barrier()
; #define PG8_SCHED __builtin_amdgcn_sched_barrier(0)
; template <class Epi>
; __device__ __forceinline__ void gemm_phase(LAS unsigned char* lds, const Gemm g, const Order& S, const Epi& E) {
;     ...
;             PG8_LDA(At, 1, 1); PG8_STAGE(PG8_SB(1, 0), b3, voffB); PG8_STAGE(PG8_SB(1, 1), b3 + hstepB, voffB); PG8_STAGE(PG8_SA(1, 0), a3, voffA);
;             PG8_WAIT_V(8); PG8_WAIT_L(0); PG8_BAR; PG8_MMA(1, 0, At, B0); PG8_MMA(1, 1, At, B1); PG8_BAR; PG8_SCHED;
;         }
;         if constexpr (ALIGN_EPI) { if (wr == 0) PG8_BAR; }
;         if constexpr (!Epi::AFTER_DRAIN) E(acc, cur, wr, wc, fr, fq);
;         if (!has_next) break;
	s_add_i32 s4, s4, s1
	v_lshl_add_u64 v[138:139], v[138:139], 0, s[62:63]
	s_mov_b32 m0, s4
	ds_read_b128 v[188:191], v143 offset:49152
	ds_read_b128 v[192:195], v143 offset:50176
	ds_read_b128 v[214:217], v143 offset:51200
	ds_read_b128 v[218:221], v143 offset:52224
	ds_read_b128 v[222:225], v143 offset:53248
	ds_read_b128 v[226:229], v143 offset:54272
	ds_read_b128 v[230:233], v143 offset:55296
	ds_read_b128 v[234:237], v143 offset:56320
	global_load_lds_dwordx4 v[138:139], off
	s_add_i32 m0, s4, 0x2000
	s_add_u32 s36, s50, 0x40080
	v_lshl_add_u64 v[138:139], v[238:239], 0, s[62:63]
	s_addc_u32 s37, s51, 0
	s_add_i32 s4, s5, s1
	global_load_lds_dwordx4 v[138:139], off
	v_lshl_add_u64 v[138:139], s[36:37], 0, v[160:161]
	s_mov_b32 m0, s4
	s_nop 0
	global_load_lds_dwordx4 v[138:139], off
	v_lshl_add_u64 v[138:139], s[36:37], 0, v[128:129]
	s_add_i32 m0, s4, 0x2000
	s_nop 0
	global_load_lds_dwordx4 v[138:139], off
	v_lshl_add_u64 v[138:139], v[240:241], 0, s[62:63]
	s_mov_b32 m0, s25
	s_nop 0
	global_load_lds_dwordx4 v[138:139], off
	v_lshl_add_u64 v[138:139], v[242:243], 0, s[62:63]
	s_mov_b32 m0, s26
	s_nop 0
	global_load_lds_dwordx4 v[138:139], off
	s_waitcnt vmcnt(8)
	s_waitcnt lgkmcnt(0)
	s_barrier
	s_setprio 1
	s_waitcnt lgkmcnt(0)
	v_mfma_f32_16x16x32_bf16 v[60:63], v[144:147], v[188:191], v[60:63]
	v_mfma_f32_16x16x32_bf16 v[56:59], v[152:155], v[188:191], v[56:59]
	v_mfma_f32_16x16x32_bf16 v[52:55], v[144:147], v[214:217], v[52:55]
	v_mfma_f32_16x16x32_bf16 v[44:47], v[152:155], v[214:217], v[44:47]
	v_mfma_f32_16x16x32_bf16 v[36:39], v[144:147], v[222:225], v[36:39]
	v_mfma_f32_16x16x32_bf16 v[28:31], v[152:155], v[222:225], v[28:31]
	v_mfma_f32_16x16x32_bf16 v[20:23], v[144:147], v[230:233], v[20:23]
	v_mfma_f32_16x16x32_bf16 v[12:15], v[152:155], v[230:233], v[12:15]
	v_mfma_f32_16x16x32_bf16 v[60:63], v[148:151], v[192:195], v[60:63]
	v_mfma_f32_16x16x32_bf16 v[56:59], v[156:159], v[192:195], v[56:59]
	v_mfma_f32_16x16x32_bf16 v[52:55], v[148:151], v[218:221], v[52:55]
	v_mfma_f32_16x16x32_bf16 v[44:47], v[156:159], v[218:221], v[44:47]
	v_mfma_f32_16x16x32_bf16 v[36:39], v[148:151], v[226:229], v[36:39]
	v_mfma_f32_16x16x32_bf16 v[28:31], v[156:159], v[226:229], v[28:31]
	v_mfma_f32_16x16x32_bf16 v[20:23], v[148:151], v[234:237], v[20:23]
	v_mfma_f32_16x16x32_bf16 v[12:15], v[156:159], v[234:237], v[12:15]
	v_mfma_f32_16x16x32_bf16 v[48:51], v[172:175], v[188:191], v[48:51]
	v_mfma_f32_16x16x32_bf16 v[40:43], v[180:183], v[188:191], v[40:43]
	v_mfma_f32_16x16x32_bf16 v[32:35], v[172:175], v[214:217], v[32:35]
	v_mfma_f32_16x16x32_bf16 v[24:27], v[180:183], v[214:217], v[24:27]
	v_mfma_f32_16x16x32_bf16 v[16:19], v[172:175], v[222:225], v[16:19]
	v_mfma_f32_16x16x32_bf16 v[8:11], v[180:183], v[222:225], v[8:11]
	v_mfma_f32_16x16x32_bf16 v[4:7], v[172:175], v[230:233], v[4:7]
	v_mfma_f32_16x16x32_bf16 v[0:3], v[180:183], v[230:233], v[0:3]
	v_mfma_f32_16x16x32_bf16 v[48:51], v[176:179], v[192:195], v[48:51]
	v_mfma_f32_16x16x32_bf16 v[40:43], v[184:187], v[192:195], v[40:43]
	v_mfma_f32_16x16x32_bf16 v[32:35], v[176:179], v[218:221], v[32:35]
	v_mfma_f32_16x16x32_bf16 v[24:27], v[184:187], v[218:221], v[24:27]
	v_mfma_f32_16x16x32_bf16 v[16:19], v[176:179], v[226:229], v[16:19]
	v_mfma_f32_16x16x32_bf16 v[8:11], v[184:187], v[226:229], v[8:11]
	v_mfma_f32_16x16x32_bf16 v[4:7], v[176:179], v[234:237], v[4:7]
	v_mfma_f32_16x16x32_bf16 v[0:3], v[184:187], v[234:237], v[0:3]
	s_setprio 0
	s_barrier
	s_add_i32 s66, s66, 2
	s_add_u32 s48, s48, 0x100
	s_addc_u32 s49, s49, 0
	s_add_u32 s41, s41, 0x100
	s_addc_u32 s43, s43, 0
	s_cmp_gt_u32 s66, 13
	s_cbranch_scc0 .LBB0_413
	s_and_b64 vcc, exec, s[12:13]
	s_cbranch_vccz .LBB0_416
	s_barrier
